# EpiRes epilogues (4 GEMMs): residual loads issued two row-blocks ahead into spare registers instead of one
# speedup vs baseline: 1.0049x; 1.0049x over previous
; #define EPI_IT_ROW(it) EPI_ROW((it) >> 2, (it) & 3)
; #define EPI_PACK8(v0, v1) (u32x4){pk2((v0)[0], (v0)[1]), pk2((v0)[2], (v0)[3]), pk2((v1)[0], (v1)[1]), pk2((v1)[2], (v1)[3])}
;     __device__ __forceinline__ void operator()(AccRef acc, const Unit& u, int wr, int wc, int fr, int fq) const {
;     ...
;         f32x4 xc[2][2], xn[2][2];
; #pragma unroll
;         for (int bj = 0; bj < 2; ++bj) { const size_t p = (size_t)EPI_IT_ROW(0) * DM + EPI_COL(bj); xc[bj][0] = *(const f32x4*)(xin + p); xc[bj][1] = *(const f32x4*)(xin + p + 4); }
; #pragma unroll
;         for (int it = 0; it < 8; ++it) { const int ai = it >> 2, m = it & 3, row = EPI_IT_ROW(it);
;             if (it + 1 < 8) {
; #pragma unroll
;                 for (int bj = 0; bj < 2; ++bj) { const size_t p = (size_t)EPI_IT_ROW(it + 1) * DM + EPI_COL(bj); xn[bj][0] = *(const f32x4*)(xin + p); xn[bj][1] = *(const f32x4*)(xin + p + 4); } }
;             float q = 0.f;
; #pragma unroll
;             for (int bj = 0; bj < 2; ++bj) { const size_t p = (size_t)row * DM + EPI_COL(bj);
;                 const f32x4 x0 = xc[bj][0] + acc[ai][bj][m][0], x1 = xc[bj][1] + acc[ai][bj][m][1];
;                 __builtin_nontemporal_store(x0, (f32x4*)(xout + p)); __builtin_nontemporal_store(x1, (f32x4*)(xout + p + 4));
;                 *(u32x4*)(xb + p) = EPI_PACK8(x0, x1);
;                 q += EPI_SQ8(x0, x1); }
;             q += __shfl_xor(q, 16); q += __shfl_xor(q, 32);
;             if (fq == 0) atomicAdd(ssout + row, q);
.LBB0_460:
	s_lshl_b32 s1, s34, 8
	v_mov_b32_e32 v128, v171
	v_mov_b32_e32 v168, v170
	s_add_i32 s1, s1, s63
	s_lshl_b32 s0, s0, 8
	s_or_b32 s0, s0, s64
	v_add_u32_e32 v164, s1, v128
	v_ashrrev_i32_e32 v165, 31, v164
	v_lshl_add_u32 v162, v168, 3, s0
	v_lshlrev_b64 v[128:129], 12, v[164:165]
	v_ashrrev_i32_e32 v163, 31, v162
	v_lshl_add_u64 v[128:129], s[16:17], 0, v[128:129]
	v_lshlrev_b64 v[130:131], 2, v[162:163]
	v_add_u32_e32 v160, 0x80, v162
	v_lshl_add_u64 v[132:133], v[128:129], 0, v[130:131]
	v_ashrrev_i32_e32 v161, 31, v160
	global_load_dwordx4 v[180:183], v[132:133], off offset:16
	global_load_dwordx4 v[184:187], v[132:133], off
	v_lshlrev_b64 v[132:133], 2, v[160:161]
	v_lshl_add_u64 v[128:129], v[128:129], 0, v[132:133]
	global_load_dwordx4 v[188:191], v[128:129], off
	global_load_dwordx4 v[192:195], v[128:129], off offset:16
	v_add_u32_e32 v166, 16, v164
	v_ashrrev_i32_e32 v167, 31, v166
	v_lshlrev_b64 v[128:129], 12, v[166:167]
	v_lshl_add_u64 v[128:129], s[16:17], 0, v[128:129]
	v_lshl_add_u64 v[130:131], v[128:129], 0, v[130:131]
	v_lshl_add_u64 v[132:133], v[128:129], 0, v[132:133]
	global_load_dwordx4 v[136:139], v[130:131], off offset:16
	global_load_dwordx4 v[140:143], v[130:131], off
	s_nop 0
	global_load_dwordx4 v[128:131], v[132:133], off offset:16
	s_nop 0
	global_load_dwordx4 v[132:135], v[132:133], off
	v_add_u32_e32 v244, 32, v164
	v_ashrrev_i32_e32 v245, 31, v244
	v_lshlrev_b64 v[246:247], 12, v[244:245]
	v_lshl_add_u64 v[246:247], s[16:17], 0, v[246:247]
	v_lshl_add_u64 v[248:249], v[162:163], 2, v[246:247]
	v_lshl_add_u64 v[250:251], v[160:161], 2, v[246:247]
	global_load_dwordx4 v[206:209], v[248:249], off offset:16
	global_load_dwordx4 v[210:213], v[248:249], off
	global_load_dwordx4 v[214:217], v[250:251], off offset:16
	global_load_dwordx4 v[218:221], v[250:251], off
	v_add_u32_e32 v244, 48, v164
	v_ashrrev_i32_e32 v245, 31, v244
	v_lshlrev_b64 v[246:247], 12, v[244:245]
	v_lshl_add_u64 v[246:247], s[16:17], 0, v[246:247]
	v_lshl_add_u64 v[248:249], v[162:163], 2, v[246:247]
	v_lshl_add_u64 v[250:251], v[160:161], 2, v[246:247]
	global_load_dwordx4 v[228:231], v[248:249], off offset:16
	global_load_dwordx4 v[232:235], v[248:249], off
	global_load_dwordx4 v[236:239], v[250:251], off offset:16
	global_load_dwordx4 v[240:243], v[250:251], off
	v_and_b32_e32 v178, 64, v177
	v_xor_b32_e32 v169, 16, v177
	v_add_u32_e32 v178, 64, v178
	v_cmp_lt_i32_e64 s[0:1], v169, v178
	v_xor_b32_e32 v179, 32, v177
	v_cmp_eq_u32_e32 vcc, 0, v168
	v_cndmask_b32_e64 v168, v177, v169, s[0:1]
	v_cmp_lt_i32_e64 s[0:1], v179, v178
	v_lshlrev_b32_e32 v178, 2, v168
	v_lshlrev_b64 v[168:169], 10, v[164:165]
	v_lshl_add_u64 v[196:197], v[168:169], 0, v[162:163]
	v_lshl_add_u64 v[198:199], v[196:197], 2, s[48:49]
	v_cndmask_b32_e64 v179, v177, v179, s[0:1]
	v_lshl_add_u64 v[168:169], v[168:169], 0, v[160:161]
	v_lshl_add_u64 v[196:197], v[196:197], 1, s[24:25]
	v_lshl_add_u64 v[200:201], v[168:169], 2, s[48:49]
	v_lshlrev_b32_e32 v179, 2, v179
	s_waitcnt vmcnt(8)
	v_pk_add_f32 v[122:123], v[122:123], v[182:183]
	v_pk_add_f32 v[126:127], v[126:127], v[186:187]
	v_pk_add_f32 v[124:125], v[124:125], v[184:185]
	v_pk_add_f32 v[118:119], v[118:119], v[190:191]
	v_pk_add_f32 v[116:117], v[116:117], v[188:189]
	v_pk_add_f32 v[120:121], v[120:121], v[180:181]
	v_pk_add_f32 v[180:181], v[112:113], v[192:193]
	global_store_dwordx4 v[198:199], v[124:127], off nt
	global_store_dwordx4 v[198:199], v[120:123], off offset:16 nt
	v_cvt_pk_bf16_f32 v112, v124, v125
	v_cvt_pk_bf16_f32 v113, v126, v127
	v_mul_f32_e32 v185, v117, v117
	v_mul_f32_e32 v125, v125, v125
	v_mul_f32_e32 v127, v127, v127
	v_mul_f32_e32 v186, v119, v119
	v_pk_add_f32 v[182:183], v[114:115], v[194:195]
	v_cvt_pk_bf16_f32 v114, v120, v121
	v_cvt_pk_bf16_f32 v115, v122, v123
	v_mul_f32_e32 v121, v121, v121
	v_mul_f32_e32 v123, v123, v123
	v_mul_f32_e32 v187, v181, v181
	v_fmac_f32_e32 v125, v124, v124
	v_fmac_f32_e32 v127, v126, v126
	v_fmac_f32_e32 v185, v116, v116
	v_fmac_f32_e32 v186, v118, v118
	v_mul_f32_e32 v188, v183, v183
	v_fmac_f32_e32 v121, v120, v120
	v_fmac_f32_e32 v123, v122, v122
	v_fmac_f32_e32 v187, v180, v180
	v_add_f32_e32 v120, v125, v127
	v_add_f32_e32 v122, v185, v186
	v_fmac_f32_e32 v188, v182, v182
	v_add_f32_e32 v120, v120, v121
	v_add_f32_e32 v121, v122, v187
	v_add_f32_e32 v120, v123, v120
	v_add_f32_e32 v121, v188, v121
	v_add_f32_e32 v120, v120, v121
	ds_bpermute_b32 v121, v178, v120
	global_store_dwordx4 v[196:197], v[112:115], off
	global_store_dwordx4 v[200:201], v[116:119], off nt
	global_store_dwordx4 v[200:201], v[180:183], off offset:16 nt
	v_lshl_add_u64 v[114:115], v[168:169], 1, s[24:25]
	v_cvt_pk_bf16_f32 v184, v116, v117
	v_cvt_pk_bf16_f32 v185, v118, v119
	s_waitcnt lgkmcnt(0)
	v_add_f32_e32 v112, v120, v121
	ds_bpermute_b32 v113, v179, v112
	v_cvt_pk_bf16_f32 v186, v180, v181
	v_cvt_pk_bf16_f32 v187, v182, v183
	global_store_dwordx4 v[114:115], v[184:187], off
	s_and_saveexec_b64 s[0:1], vcc
	s_cbranch_execz .LBB0_462
	v_lshl_add_u64 v[114:115], v[164:165], 2, s[10:11]
	s_waitcnt lgkmcnt(0)
	v_add_f32_e32 v112, v112, v113
	global_atomic_add_f32 v[114:115], v112, off
; #define EPI_IT_ROW(it) EPI_ROW((it) >> 2, (it) & 3)
; #define EPI_PACK8(v0, v1) (u32x4){pk2((v0)[0], (v0)[1]), pk2((v0)[2], (v0)[3]), pk2((v1)[0], (v1)[1]), pk2((v1)[2], (v1)[3])}
;     __device__ __forceinline__ void operator()(AccRef acc, const Unit& u, int wr, int wc, int fr, int fq) const {
;     ...
;         for (int it = 0; it < 8; ++it) { const int ai = it >> 2, m = it & 3, row = EPI_IT_ROW(it);
;             if (it + 1 < 8) {
; #pragma unroll
;                 for (int bj = 0; bj < 2; ++bj) { const size_t p = (size_t)EPI_IT_ROW(it + 1) * DM + EPI_COL(bj); xn[bj][0] = *(const f32x4*)(xin + p); xn[bj][1] = *(const f32x4*)(xin + p + 4); } }
;             float q = 0.f;
; #pragma unroll
;             for (int bj = 0; bj < 2; ++bj) { const size_t p = (size_t)row * DM + EPI_COL(bj);
;                 const f32x4 x0 = xc[bj][0] + acc[ai][bj][m][0], x1 = xc[bj][1] + acc[ai][bj][m][1];
;                 __builtin_nontemporal_store(x0, (f32x4*)(xout + p)); __builtin_nontemporal_store(x1, (f32x4*)(xout + p + 4));
;                 *(u32x4*)(xb + p) = EPI_PACK8(x0, x1);
;                 q += EPI_SQ8(x0, x1); }
;             q += __shfl_xor(q, 16); q += __shfl_xor(q, 32);
;             if (fq == 0) atomicAdd(ssout + row, q);
; #pragma unroll
;             for (int bj = 0; bj < 2; ++bj) { xc[bj][0] = xn[bj][0]; xc[bj][1] = xn[bj][1]; } }
.LBB0_462:
	s_or_b64 exec, exec, s[0:1]
	v_add_u32_e32 v168, 32, v164
	v_ashrrev_i32_e32 v169, 31, v168
	s_waitcnt lgkmcnt(0)
	v_lshlrev_b64 v[112:113], 12, v[168:169]
	v_lshl_add_u64 v[112:113], s[16:17], 0, v[112:113]
	v_lshl_add_u64 v[114:115], v[162:163], 2, v[112:113]
	v_lshl_add_u64 v[116:117], v[160:161], 2, v[112:113]
	s_nop 0
	s_nop 0
	v_lshlrev_b64 v[180:181], 10, v[166:167]
	v_lshl_add_u64 v[182:183], v[180:181], 0, v[162:163]
	v_pk_add_f32 v[110:111], v[110:111], v[142:143]
	v_pk_add_f32 v[108:109], v[108:109], v[140:141]
	v_pk_add_f32 v[104:105], v[104:105], v[136:137]
	v_lshl_add_u64 v[136:137], v[182:183], 2, s[48:49]
	v_pk_add_f32 v[106:107], v[106:107], v[138:139]
	global_store_dwordx4 v[136:137], v[108:111], off nt
	global_store_dwordx4 v[136:137], v[104:107], off offset:16 nt
	v_cvt_pk_bf16_f32 v136, v108, v109
	v_cvt_pk_bf16_f32 v138, v104, v105
	v_pk_add_f32 v[102:103], v[102:103], v[134:135]
	v_mul_f32_e32 v109, v109, v109
	v_fmac_f32_e32 v109, v108, v108
	v_mul_f32_e32 v108, v111, v111
	v_fmac_f32_e32 v108, v110, v110
	v_mul_f32_e32 v105, v105, v105
	v_add_f32_e32 v108, v109, v108
	v_fmac_f32_e32 v105, v104, v104
	v_add_f32_e32 v104, v108, v105
	v_mul_f32_e32 v105, v107, v107
	v_pk_add_f32 v[100:101], v[100:101], v[132:133]
	v_cvt_pk_bf16_f32 v139, v106, v107
	v_fmac_f32_e32 v105, v106, v106
	v_pk_add_f32 v[106:107], v[98:99], v[130:131]
	v_mul_f32_e32 v98, v101, v101
	v_mul_f32_e32 v99, v103, v103
	v_cvt_pk_bf16_f32 v137, v110, v111
	v_add_f32_e32 v110, v105, v104
	v_pk_add_f32 v[104:105], v[96:97], v[128:129]
	v_fmac_f32_e32 v98, v100, v100
	v_fmac_f32_e32 v99, v102, v102
	v_add_f32_e32 v98, v98, v99
	v_mul_f32_e32 v99, v105, v105
	v_fmac_f32_e32 v99, v104, v104
	v_add_f32_e32 v98, v98, v99
	v_mul_f32_e32 v99, v107, v107
	v_fmac_f32_e32 v99, v106, v106
	v_add_f32_e32 v98, v99, v98
	v_add_f32_e32 v110, v110, v98
	ds_bpermute_b32 v111, v178, v110
	v_lshl_add_u64 v[108:109], v[180:181], 0, v[160:161]
	v_lshl_add_u64 v[140:141], v[182:183], 1, s[24:25]
	v_lshl_add_u64 v[96:97], v[108:109], 2, s[48:49]
	global_store_dwordx4 v[140:141], v[136:139], off
	global_store_dwordx4 v[96:97], v[100:103], off nt
	global_store_dwordx4 v[96:97], v[104:107], off offset:16 nt
	s_waitcnt lgkmcnt(0)
	v_add_f32_e32 v96, v110, v111
	ds_bpermute_b32 v97, v179, v96
	v_cvt_pk_bf16_f32 v99, v102, v103
	v_lshl_add_u64 v[102:103], v[108:109], 1, s[24:25]
	v_cvt_pk_bf16_f32 v98, v100, v101
	v_cvt_pk_bf16_f32 v100, v104, v105
	v_cvt_pk_bf16_f32 v101, v106, v107
	global_store_dwordx4 v[102:103], v[98:101], off
	s_and_saveexec_b64 s[0:1], vcc
	s_cbranch_execz .LBB0_464
	v_lshl_add_u64 v[98:99], v[166:167], 2, s[10:11]
	s_waitcnt lgkmcnt(0)
	v_add_f32_e32 v96, v96, v97
	global_atomic_add_f32 v[98:99], v96, off
.LBB0_464:
	s_or_b64 exec, exec, s[0:1]
	s_waitcnt vmcnt(16)
	v_mov_b64_e32 v[120:121], v[206:207]
	v_mov_b64_e32 v[122:123], v[208:209]
	v_mov_b64_e32 v[124:125], v[210:211]
	v_mov_b64_e32 v[126:127], v[212:213]
	v_mov_b64_e32 v[112:113], v[214:215]
	v_mov_b64_e32 v[114:115], v[216:217]
	v_mov_b64_e32 v[116:117], v[218:219]
	v_mov_b64_e32 v[118:119], v[220:221]
	v_add_u32_e32 v244, 128, v164
	v_ashrrev_i32_e32 v245, 31, v244
	v_lshlrev_b64 v[246:247], 12, v[244:245]
	v_lshl_add_u64 v[246:247], s[16:17], 0, v[246:247]
	v_lshl_add_u64 v[248:249], v[162:163], 2, v[246:247]
	v_lshl_add_u64 v[250:251], v[160:161], 2, v[246:247]
	global_load_dwordx4 v[206:209], v[248:249], off offset:16
	global_load_dwordx4 v[210:213], v[248:249], off
	global_load_dwordx4 v[214:217], v[250:251], off offset:16
	global_load_dwordx4 v[218:221], v[250:251], off
	v_add_u32_e32 v128, 48, v164
	v_ashrrev_i32_e32 v129, 31, v128
	s_waitcnt lgkmcnt(0)
	v_lshlrev_b64 v[96:97], 12, v[128:129]
	v_lshl_add_u64 v[96:97], s[16:17], 0, v[96:97]
	v_lshl_add_u64 v[98:99], v[162:163], 2, v[96:97]
	v_lshl_add_u64 v[100:101], v[160:161], 2, v[96:97]
	s_nop 0
	s_nop 0
	v_lshlrev_b64 v[130:131], 10, v[168:169]
	v_lshl_add_u64 v[132:133], v[130:131], 0, v[162:163]
	v_pk_add_f32 v[94:95], v[94:95], v[126:127]
	v_pk_add_f32 v[92:93], v[92:93], v[124:125]
	v_pk_add_f32 v[88:89], v[88:89], v[120:121]
	v_lshl_add_u64 v[120:121], v[132:133], 2, s[48:49]
	v_pk_add_f32 v[90:91], v[90:91], v[122:123]
	global_store_dwordx4 v[120:121], v[92:95], off nt
	global_store_dwordx4 v[120:121], v[88:91], off offset:16 nt
	v_cvt_pk_bf16_f32 v120, v92, v93
	v_cvt_pk_bf16_f32 v122, v88, v89
	v_pk_add_f32 v[86:87], v[86:87], v[118:119]
	v_mul_f32_e32 v93, v93, v93
	v_fmac_f32_e32 v93, v92, v92
	v_mul_f32_e32 v92, v95, v95
	v_fmac_f32_e32 v92, v94, v94
	v_mul_f32_e32 v89, v89, v89
	v_add_f32_e32 v92, v93, v92
	v_fmac_f32_e32 v89, v88, v88
	v_add_f32_e32 v88, v92, v89
	v_mul_f32_e32 v89, v91, v91
	v_pk_add_f32 v[84:85], v[84:85], v[116:117]
	v_cvt_pk_bf16_f32 v123, v90, v91
	v_fmac_f32_e32 v89, v90, v90
	v_pk_add_f32 v[90:91], v[82:83], v[114:115]
	v_mul_f32_e32 v82, v85, v85
	v_mul_f32_e32 v83, v87, v87
	v_cvt_pk_bf16_f32 v121, v94, v95
	v_add_f32_e32 v94, v89, v88
	v_pk_add_f32 v[88:89], v[80:81], v[112:113]
	v_fmac_f32_e32 v82, v84, v84
	v_fmac_f32_e32 v83, v86, v86
	v_add_f32_e32 v82, v82, v83
	v_mul_f32_e32 v83, v89, v89
	v_fmac_f32_e32 v83, v88, v88
	v_add_f32_e32 v82, v82, v83
	v_mul_f32_e32 v83, v91, v91
	v_fmac_f32_e32 v83, v90, v90
	v_add_f32_e32 v82, v83, v82
	v_add_f32_e32 v94, v94, v82
	ds_bpermute_b32 v95, v178, v94
	v_lshl_add_u64 v[92:93], v[130:131], 0, v[160:161]
	v_lshl_add_u64 v[124:125], v[132:133], 1, s[24:25]
	v_lshl_add_u64 v[80:81], v[92:93], 2, s[48:49]
	global_store_dwordx4 v[124:125], v[120:123], off
	global_store_dwordx4 v[80:81], v[84:87], off nt
	global_store_dwordx4 v[80:81], v[88:91], off offset:16 nt
	s_waitcnt lgkmcnt(0)
	v_add_f32_e32 v80, v94, v95
	ds_bpermute_b32 v81, v179, v80
	v_cvt_pk_bf16_f32 v83, v86, v87
	v_lshl_add_u64 v[86:87], v[92:93], 1, s[24:25]
	v_cvt_pk_bf16_f32 v82, v84, v85
	v_cvt_pk_bf16_f32 v84, v88, v89
	v_cvt_pk_bf16_f32 v85, v90, v91
	global_store_dwordx4 v[86:87], v[82:85], off
	s_and_saveexec_b64 s[0:1], vcc
	s_cbranch_execz .LBB0_466
	v_lshl_add_u64 v[82:83], v[168:169], 2, s[10:11]
	s_waitcnt lgkmcnt(0)
	v_add_f32_e32 v80, v80, v81
	global_atomic_add_f32 v[82:83], v80, off
; #define EPI_IT_ROW(it) EPI_ROW((it) >> 2, (it) & 3)
; #define EPI_PACK8(v0, v1) (u32x4){pk2((v0)[0], (v0)[1]), pk2((v0)[2], (v0)[3]), pk2((v1)[0], (v1)[1]), pk2((v1)[2], (v1)[3])}
;     __device__ __forceinline__ void operator()(AccRef acc, const Unit& u, int wr, int wc, int fr, int fq) const {
;     ...
;         for (int it = 0; it < 8; ++it) { const int ai = it >> 2, m = it & 3, row = EPI_IT_ROW(it);
;             if (it + 1 < 8) {
; #pragma unroll
;                 for (int bj = 0; bj < 2; ++bj) { const size_t p = (size_t)EPI_IT_ROW(it + 1) * DM + EPI_COL(bj); xn[bj][0] = *(const f32x4*)(xin + p); xn[bj][1] = *(const f32x4*)(xin + p + 4); } }
;             float q = 0.f;
; #pragma unroll
;             for (int bj = 0; bj < 2; ++bj) { const size_t p = (size_t)row * DM + EPI_COL(bj);
;                 const f32x4 x0 = xc[bj][0] + acc[ai][bj][m][0], x1 = xc[bj][1] + acc[ai][bj][m][1];
;                 __builtin_nontemporal_store(x0, (f32x4*)(xout + p)); __builtin_nontemporal_store(x1, (f32x4*)(xout + p + 4));
;                 *(u32x4*)(xb + p) = EPI_PACK8(x0, x1);
;                 q += EPI_SQ8(x0, x1); }
;             q += __shfl_xor(q, 16); q += __shfl_xor(q, 32);
;             if (fq == 0) atomicAdd(ssout + row, q);
; #pragma unroll
;             for (int bj = 0; bj < 2; ++bj) { xc[bj][0] = xn[bj][0]; xc[bj][1] = xn[bj][1]; } }
.LBB0_466:
	s_or_b64 exec, exec, s[0:1]
	s_waitcnt vmcnt(22)
	v_mov_b64_e32 v[104:105], v[228:229]
	v_mov_b64_e32 v[106:107], v[230:231]
	v_mov_b64_e32 v[108:109], v[232:233]
	v_mov_b64_e32 v[110:111], v[234:235]
	v_mov_b64_e32 v[96:97], v[236:237]
	v_mov_b64_e32 v[98:99], v[238:239]
	v_mov_b64_e32 v[100:101], v[240:241]
	v_mov_b64_e32 v[102:103], v[242:243]
	v_add_u32_e32 v244, 144, v164
	v_ashrrev_i32_e32 v245, 31, v244
	v_lshlrev_b64 v[246:247], 12, v[244:245]
	v_lshl_add_u64 v[246:247], s[16:17], 0, v[246:247]
	v_lshl_add_u64 v[248:249], v[162:163], 2, v[246:247]
	v_lshl_add_u64 v[250:251], v[160:161], 2, v[246:247]
	global_load_dwordx4 v[228:231], v[248:249], off offset:16
	global_load_dwordx4 v[232:235], v[248:249], off
	global_load_dwordx4 v[236:239], v[250:251], off offset:16
	global_load_dwordx4 v[240:243], v[250:251], off
	v_add_u32_e32 v112, 0x80, v164
	v_ashrrev_i32_e32 v113, 31, v112
	s_waitcnt lgkmcnt(0)
	v_lshlrev_b64 v[80:81], 12, v[112:113]
	v_lshl_add_u64 v[80:81], s[16:17], 0, v[80:81]
	v_lshl_add_u64 v[82:83], v[162:163], 2, v[80:81]
	v_lshl_add_u64 v[84:85], v[160:161], 2, v[80:81]
	s_nop 0
	s_nop 0
	v_lshlrev_b64 v[114:115], 10, v[128:129]
	v_lshl_add_u64 v[116:117], v[114:115], 0, v[162:163]
	v_pk_add_f32 v[78:79], v[78:79], v[110:111]
	v_pk_add_f32 v[76:77], v[76:77], v[108:109]
	v_pk_add_f32 v[72:73], v[72:73], v[104:105]
	v_lshl_add_u64 v[104:105], v[116:117], 2, s[48:49]
	v_pk_add_f32 v[74:75], v[74:75], v[106:107]
	global_store_dwordx4 v[104:105], v[76:79], off nt
	global_store_dwordx4 v[104:105], v[72:75], off offset:16 nt
	v_cvt_pk_bf16_f32 v104, v76, v77
	v_cvt_pk_bf16_f32 v106, v72, v73
	v_pk_add_f32 v[70:71], v[70:71], v[102:103]
	v_mul_f32_e32 v77, v77, v77
	v_fmac_f32_e32 v77, v76, v76
	v_mul_f32_e32 v76, v79, v79
	v_fmac_f32_e32 v76, v78, v78
	v_mul_f32_e32 v73, v73, v73
	v_add_f32_e32 v76, v77, v76
	v_fmac_f32_e32 v73, v72, v72
	v_add_f32_e32 v72, v76, v73
	v_mul_f32_e32 v73, v75, v75
	v_pk_add_f32 v[68:69], v[68:69], v[100:101]
	v_cvt_pk_bf16_f32 v107, v74, v75
	v_fmac_f32_e32 v73, v74, v74
	v_pk_add_f32 v[74:75], v[66:67], v[98:99]
	v_mul_f32_e32 v66, v69, v69
	v_mul_f32_e32 v67, v71, v71
	v_cvt_pk_bf16_f32 v105, v78, v79
	v_add_f32_e32 v78, v73, v72
	v_pk_add_f32 v[72:73], v[64:65], v[96:97]
	v_fmac_f32_e32 v66, v68, v68
	v_fmac_f32_e32 v67, v70, v70
	v_add_f32_e32 v66, v66, v67
	v_mul_f32_e32 v67, v73, v73
	v_fmac_f32_e32 v67, v72, v72
	v_add_f32_e32 v66, v66, v67
	v_mul_f32_e32 v67, v75, v75
	v_fmac_f32_e32 v67, v74, v74
	v_add_f32_e32 v66, v67, v66
	v_add_f32_e32 v78, v78, v66
	ds_bpermute_b32 v79, v178, v78
	v_lshl_add_u64 v[76:77], v[114:115], 0, v[160:161]
	v_lshl_add_u64 v[108:109], v[116:117], 1, s[24:25]
	v_lshl_add_u64 v[64:65], v[76:77], 2, s[48:49]
	global_store_dwordx4 v[108:109], v[104:107], off
	global_store_dwordx4 v[64:65], v[68:71], off nt
	global_store_dwordx4 v[64:65], v[72:75], off offset:16 nt
	s_waitcnt lgkmcnt(0)
	v_add_f32_e32 v64, v78, v79
	ds_bpermute_b32 v65, v179, v64
	v_cvt_pk_bf16_f32 v67, v70, v71
	v_lshl_add_u64 v[70:71], v[76:77], 1, s[24:25]
	v_cvt_pk_bf16_f32 v66, v68, v69
	v_cvt_pk_bf16_f32 v68, v72, v73
	v_cvt_pk_bf16_f32 v69, v74, v75
	global_store_dwordx4 v[70:71], v[66:69], off
	s_and_saveexec_b64 s[0:1], vcc
	s_cbranch_execz .LBB0_468
	v_lshl_add_u64 v[66:67], v[128:129], 2, s[10:11]
	s_waitcnt lgkmcnt(0)
	v_add_f32_e32 v64, v64, v65
	global_atomic_add_f32 v[66:67], v64, off
.LBB0_468:
	s_or_b64 exec, exec, s[0:1]
	s_waitcnt vmcnt(16)
	v_mov_b64_e32 v[88:89], v[206:207]
	v_mov_b64_e32 v[90:91], v[208:209]
	v_mov_b64_e32 v[92:93], v[210:211]
	v_mov_b64_e32 v[94:95], v[212:213]
	v_mov_b64_e32 v[80:81], v[214:215]
	v_mov_b64_e32 v[82:83], v[216:217]
	v_mov_b64_e32 v[84:85], v[218:219]
	v_mov_b64_e32 v[86:87], v[220:221]
	v_add_u32_e32 v244, 160, v164
	v_ashrrev_i32_e32 v245, 31, v244
	v_lshlrev_b64 v[246:247], 12, v[244:245]
	v_lshl_add_u64 v[246:247], s[16:17], 0, v[246:247]
	v_lshl_add_u64 v[248:249], v[162:163], 2, v[246:247]
	v_lshl_add_u64 v[250:251], v[160:161], 2, v[246:247]
	global_load_dwordx4 v[206:209], v[248:249], off offset:16
	global_load_dwordx4 v[210:213], v[248:249], off
	global_load_dwordx4 v[214:217], v[250:251], off offset:16
	global_load_dwordx4 v[218:221], v[250:251], off
	v_add_u32_e32 v96, 0x90, v164
	v_ashrrev_i32_e32 v97, 31, v96
	s_waitcnt lgkmcnt(0)
	v_lshlrev_b64 v[64:65], 12, v[96:97]
	v_lshl_add_u64 v[64:65], s[16:17], 0, v[64:65]
	v_lshl_add_u64 v[66:67], v[162:163], 2, v[64:65]
	v_lshl_add_u64 v[68:69], v[160:161], 2, v[64:65]
	s_nop 0
	s_nop 0
	v_lshlrev_b64 v[98:99], 10, v[112:113]
	v_lshl_add_u64 v[100:101], v[98:99], 0, v[162:163]
	v_pk_add_f32 v[62:63], v[62:63], v[94:95]
	v_pk_add_f32 v[60:61], v[60:61], v[92:93]
	v_pk_add_f32 v[56:57], v[56:57], v[88:89]
	v_lshl_add_u64 v[88:89], v[100:101], 2, s[48:49]
	v_pk_add_f32 v[58:59], v[58:59], v[90:91]
	global_store_dwordx4 v[88:89], v[60:63], off nt
	global_store_dwordx4 v[88:89], v[56:59], off offset:16 nt
	v_cvt_pk_bf16_f32 v88, v60, v61
	v_cvt_pk_bf16_f32 v90, v56, v57
	v_pk_add_f32 v[54:55], v[54:55], v[86:87]
	v_mul_f32_e32 v61, v61, v61
	v_fmac_f32_e32 v61, v60, v60
	v_mul_f32_e32 v60, v63, v63
	v_fmac_f32_e32 v60, v62, v62
	v_mul_f32_e32 v57, v57, v57
	v_add_f32_e32 v60, v61, v60
	v_fmac_f32_e32 v57, v56, v56
	v_add_f32_e32 v56, v60, v57
	v_mul_f32_e32 v57, v59, v59
	v_pk_add_f32 v[52:53], v[52:53], v[84:85]
	v_cvt_pk_bf16_f32 v91, v58, v59
	v_fmac_f32_e32 v57, v58, v58
	v_pk_add_f32 v[58:59], v[50:51], v[82:83]
	v_mul_f32_e32 v50, v53, v53
	v_mul_f32_e32 v51, v55, v55
	v_cvt_pk_bf16_f32 v89, v62, v63
	v_add_f32_e32 v62, v57, v56
	v_pk_add_f32 v[56:57], v[48:49], v[80:81]
	v_fmac_f32_e32 v50, v52, v52
	v_fmac_f32_e32 v51, v54, v54
	v_add_f32_e32 v50, v50, v51
	v_mul_f32_e32 v51, v57, v57
	v_fmac_f32_e32 v51, v56, v56
	v_add_f32_e32 v50, v50, v51
	v_mul_f32_e32 v51, v59, v59
	v_fmac_f32_e32 v51, v58, v58
	v_add_f32_e32 v50, v51, v50
	v_add_f32_e32 v62, v62, v50
	ds_bpermute_b32 v63, v178, v62
	v_lshl_add_u64 v[60:61], v[98:99], 0, v[160:161]
	v_lshl_add_u64 v[92:93], v[100:101], 1, s[24:25]
	v_lshl_add_u64 v[48:49], v[60:61], 2, s[48:49]
	global_store_dwordx4 v[92:93], v[88:91], off
	global_store_dwordx4 v[48:49], v[52:55], off nt
	global_store_dwordx4 v[48:49], v[56:59], off offset:16 nt
	s_waitcnt lgkmcnt(0)
	v_add_f32_e32 v48, v62, v63
	ds_bpermute_b32 v49, v179, v48
	v_cvt_pk_bf16_f32 v51, v54, v55
	v_lshl_add_u64 v[54:55], v[60:61], 1, s[24:25]
	v_cvt_pk_bf16_f32 v50, v52, v53
	v_cvt_pk_bf16_f32 v52, v56, v57
	v_cvt_pk_bf16_f32 v53, v58, v59
	global_store_dwordx4 v[54:55], v[50:53], off
	s_and_saveexec_b64 s[0:1], vcc
	s_cbranch_execz .LBB0_470
	v_lshl_add_u64 v[50:51], v[112:113], 2, s[10:11]
	s_waitcnt lgkmcnt(0)
	v_add_f32_e32 v48, v48, v49
	global_atomic_add_f32 v[50:51], v48, off
; #define EPI_IT_ROW(it) EPI_ROW((it) >> 2, (it) & 3)
; #define EPI_PACK8(v0, v1) (u32x4){pk2((v0)[0], (v0)[1]), pk2((v0)[2], (v0)[3]), pk2((v1)[0], (v1)[1]), pk2((v1)[2], (v1)[3])}
;     __device__ __forceinline__ void operator()(AccRef acc, const Unit& u, int wr, int wc, int fr, int fq) const {
;     ...
;         for (int it = 0; it < 8; ++it) { const int ai = it >> 2, m = it & 3, row = EPI_IT_ROW(it);
;             if (it + 1 < 8) {
; #pragma unroll
;                 for (int bj = 0; bj < 2; ++bj) { const size_t p = (size_t)EPI_IT_ROW(it + 1) * DM + EPI_COL(bj); xn[bj][0] = *(const f32x4*)(xin + p); xn[bj][1] = *(const f32x4*)(xin + p + 4); } }
;             float q = 0.f;
; #pragma unroll
;             for (int bj = 0; bj < 2; ++bj) { const size_t p = (size_t)row * DM + EPI_COL(bj);
;                 const f32x4 x0 = xc[bj][0] + acc[ai][bj][m][0], x1 = xc[bj][1] + acc[ai][bj][m][1];
;                 __builtin_nontemporal_store(x0, (f32x4*)(xout + p)); __builtin_nontemporal_store(x1, (f32x4*)(xout + p + 4));
;                 *(u32x4*)(xb + p) = EPI_PACK8(x0, x1);
;                 q += EPI_SQ8(x0, x1); }
;             q += __shfl_xor(q, 16); q += __shfl_xor(q, 32);
;             if (fq == 0) atomicAdd(ssout + row, q);
; #pragma unroll
;             for (int bj = 0; bj < 2; ++bj) { xc[bj][0] = xn[bj][0]; xc[bj][1] = xn[bj][1]; } }
.LBB0_470:
	s_or_b64 exec, exec, s[0:1]
	s_waitcnt vmcnt(16)
	v_mov_b64_e32 v[72:73], v[228:229]
	v_mov_b64_e32 v[74:75], v[230:231]
	v_mov_b64_e32 v[76:77], v[232:233]
	v_mov_b64_e32 v[78:79], v[234:235]
	v_mov_b64_e32 v[64:65], v[236:237]
	v_mov_b64_e32 v[66:67], v[238:239]
	v_mov_b64_e32 v[68:69], v[240:241]
	v_mov_b64_e32 v[70:71], v[242:243]
	v_add_u32_e32 v244, 176, v164
	v_ashrrev_i32_e32 v245, 31, v244
	v_lshlrev_b64 v[246:247], 12, v[244:245]
	v_lshl_add_u64 v[246:247], s[16:17], 0, v[246:247]
	v_lshl_add_u64 v[248:249], v[162:163], 2, v[246:247]
	v_lshl_add_u64 v[250:251], v[160:161], 2, v[246:247]
	global_load_dwordx4 v[228:231], v[248:249], off offset:16
	global_load_dwordx4 v[232:235], v[248:249], off
	global_load_dwordx4 v[236:239], v[250:251], off offset:16
	global_load_dwordx4 v[240:243], v[250:251], off
	v_add_u32_e32 v80, 0xa0, v164
	v_ashrrev_i32_e32 v81, 31, v80
	s_waitcnt lgkmcnt(0)
	v_lshlrev_b64 v[48:49], 12, v[80:81]
	v_lshl_add_u64 v[48:49], s[16:17], 0, v[48:49]
	v_lshl_add_u64 v[50:51], v[162:163], 2, v[48:49]
	v_lshl_add_u64 v[52:53], v[160:161], 2, v[48:49]
	s_nop 0
	s_nop 0
	v_lshlrev_b64 v[82:83], 10, v[96:97]
	v_lshl_add_u64 v[84:85], v[82:83], 0, v[162:163]
	v_pk_add_f32 v[46:47], v[46:47], v[78:79]
	v_pk_add_f32 v[44:45], v[44:45], v[76:77]
	v_pk_add_f32 v[40:41], v[40:41], v[72:73]
	v_lshl_add_u64 v[72:73], v[84:85], 2, s[48:49]
	v_pk_add_f32 v[42:43], v[42:43], v[74:75]
	global_store_dwordx4 v[72:73], v[44:47], off nt
	global_store_dwordx4 v[72:73], v[40:43], off offset:16 nt
	v_cvt_pk_bf16_f32 v72, v44, v45
	v_cvt_pk_bf16_f32 v74, v40, v41
	v_pk_add_f32 v[38:39], v[38:39], v[70:71]
	v_mul_f32_e32 v45, v45, v45
	v_fmac_f32_e32 v45, v44, v44
	v_mul_f32_e32 v44, v47, v47
	v_fmac_f32_e32 v44, v46, v46
	v_mul_f32_e32 v41, v41, v41
	v_add_f32_e32 v44, v45, v44
	v_fmac_f32_e32 v41, v40, v40
	v_add_f32_e32 v40, v44, v41
	v_mul_f32_e32 v41, v43, v43
	v_pk_add_f32 v[36:37], v[36:37], v[68:69]
	v_cvt_pk_bf16_f32 v75, v42, v43
	v_fmac_f32_e32 v41, v42, v42
	v_pk_add_f32 v[42:43], v[34:35], v[66:67]
	v_mul_f32_e32 v34, v37, v37
	v_mul_f32_e32 v35, v39, v39
	v_cvt_pk_bf16_f32 v73, v46, v47
	v_add_f32_e32 v46, v41, v40
	v_pk_add_f32 v[40:41], v[32:33], v[64:65]
	v_fmac_f32_e32 v34, v36, v36
	v_fmac_f32_e32 v35, v38, v38
	v_add_f32_e32 v34, v34, v35
	v_mul_f32_e32 v35, v41, v41
	v_fmac_f32_e32 v35, v40, v40
	v_add_f32_e32 v34, v34, v35
	v_mul_f32_e32 v35, v43, v43
	v_fmac_f32_e32 v35, v42, v42
	v_add_f32_e32 v34, v35, v34
	v_add_f32_e32 v46, v46, v34
	ds_bpermute_b32 v47, v178, v46
	v_lshl_add_u64 v[44:45], v[82:83], 0, v[160:161]
	v_lshl_add_u64 v[76:77], v[84:85], 1, s[24:25]
	v_lshl_add_u64 v[32:33], v[44:45], 2, s[48:49]
	global_store_dwordx4 v[76:77], v[72:75], off
	global_store_dwordx4 v[32:33], v[36:39], off nt
	global_store_dwordx4 v[32:33], v[40:43], off offset:16 nt
	s_waitcnt lgkmcnt(0)
	v_add_f32_e32 v32, v46, v47
	ds_bpermute_b32 v33, v179, v32
	v_cvt_pk_bf16_f32 v35, v38, v39
	v_lshl_add_u64 v[38:39], v[44:45], 1, s[24:25]
	v_cvt_pk_bf16_f32 v34, v36, v37
	v_cvt_pk_bf16_f32 v36, v40, v41
	v_cvt_pk_bf16_f32 v37, v42, v43
	global_store_dwordx4 v[38:39], v[34:37], off
	s_and_saveexec_b64 s[0:1], vcc
	s_cbranch_execz .LBB0_472
	v_lshl_add_u64 v[34:35], v[96:97], 2, s[10:11]
	s_waitcnt lgkmcnt(0)
	v_add_f32_e32 v32, v32, v33
	global_atomic_add_f32 v[34:35], v32, off
; #define EPI_IT_ROW(it) EPI_ROW((it) >> 2, (it) & 3)
; #define EPI_PACK8(v0, v1) (u32x4){pk2((v0)[0], (v0)[1]), pk2((v0)[2], (v0)[3]), pk2((v1)[0], (v1)[1]), pk2((v1)[2], (v1)[3])}
;     __device__ __forceinline__ void operator()(AccRef acc, const Unit& u, int wr, int wc, int fr, int fq) const {
;     ...
;         for (int it = 0; it < 8; ++it) { const int ai = it >> 2, m = it & 3, row = EPI_IT_ROW(it);
;             if (it + 1 < 8) {
; #pragma unroll
;                 for (int bj = 0; bj < 2; ++bj) { const size_t p = (size_t)EPI_IT_ROW(it + 1) * DM + EPI_COL(bj); xn[bj][0] = *(const f32x4*)(xin + p); xn[bj][1] = *(const f32x4*)(xin + p + 4); } }
;             float q = 0.f;
; #pragma unroll
;             for (int bj = 0; bj < 2; ++bj) { const size_t p = (size_t)row * DM + EPI_COL(bj);
;                 const f32x4 x0 = xc[bj][0] + acc[ai][bj][m][0], x1 = xc[bj][1] + acc[ai][bj][m][1];
;                 __builtin_nontemporal_store(x0, (f32x4*)(xout + p)); __builtin_nontemporal_store(x1, (f32x4*)(xout + p + 4));
;                 *(u32x4*)(xb + p) = EPI_PACK8(x0, x1);
;                 q += EPI_SQ8(x0, x1); }
;             q += __shfl_xor(q, 16); q += __shfl_xor(q, 32);
;             if (fq == 0) atomicAdd(ssout + row, q);
; #pragma unroll
;             for (int bj = 0; bj < 2; ++bj) { xc[bj][0] = xn[bj][0]; xc[bj][1] = xn[bj][1]; } }
.LBB0_472:
	s_or_b64 exec, exec, s[0:1]
	s_waitcnt vmcnt(16)
	v_mov_b64_e32 v[56:57], v[206:207]
	v_mov_b64_e32 v[58:59], v[208:209]
	v_mov_b64_e32 v[60:61], v[210:211]
	v_mov_b64_e32 v[62:63], v[212:213]
	v_mov_b64_e32 v[48:49], v[214:215]
	v_mov_b64_e32 v[50:51], v[216:217]
	v_mov_b64_e32 v[52:53], v[218:219]
	v_mov_b64_e32 v[54:55], v[220:221]
	v_add_u32_e32 v64, 0xb0, v164
	v_ashrrev_i32_e32 v65, 31, v64
	s_waitcnt lgkmcnt(0)
	v_lshlrev_b64 v[32:33], 12, v[64:65]
	v_lshl_add_u64 v[32:33], s[16:17], 0, v[32:33]
	v_lshl_add_u64 v[34:35], v[162:163], 2, v[32:33]
	v_lshl_add_u64 v[36:37], v[160:161], 2, v[32:33]
	s_nop 0
	s_nop 0
	v_lshlrev_b64 v[66:67], 10, v[80:81]
	v_lshl_add_u64 v[68:69], v[66:67], 0, v[162:163]
	v_pk_add_f32 v[30:31], v[30:31], v[62:63]
	v_pk_add_f32 v[28:29], v[28:29], v[60:61]
	v_pk_add_f32 v[24:25], v[24:25], v[56:57]
	v_lshl_add_u64 v[56:57], v[68:69], 2, s[48:49]
	v_pk_add_f32 v[26:27], v[26:27], v[58:59]
	global_store_dwordx4 v[56:57], v[28:31], off nt
	global_store_dwordx4 v[56:57], v[24:27], off offset:16 nt
	v_cvt_pk_bf16_f32 v56, v28, v29
	v_cvt_pk_bf16_f32 v58, v24, v25
	v_pk_add_f32 v[22:23], v[22:23], v[54:55]
	v_mul_f32_e32 v29, v29, v29
	v_fmac_f32_e32 v29, v28, v28
	v_mul_f32_e32 v28, v31, v31
	v_fmac_f32_e32 v28, v30, v30
	v_mul_f32_e32 v25, v25, v25
	v_add_f32_e32 v28, v29, v28
	v_fmac_f32_e32 v25, v24, v24
	v_add_f32_e32 v24, v28, v25
	v_mul_f32_e32 v25, v27, v27
	v_pk_add_f32 v[20:21], v[20:21], v[52:53]
	v_cvt_pk_bf16_f32 v59, v26, v27
	v_fmac_f32_e32 v25, v26, v26
	v_pk_add_f32 v[26:27], v[18:19], v[50:51]
	v_mul_f32_e32 v18, v21, v21
	v_mul_f32_e32 v19, v23, v23
	v_cvt_pk_bf16_f32 v57, v30, v31
	v_add_f32_e32 v30, v25, v24
	v_pk_add_f32 v[24:25], v[16:17], v[48:49]
	v_fmac_f32_e32 v18, v20, v20
	v_fmac_f32_e32 v19, v22, v22
	v_add_f32_e32 v18, v18, v19
	v_mul_f32_e32 v19, v25, v25
	v_fmac_f32_e32 v19, v24, v24
	v_add_f32_e32 v18, v18, v19
	v_mul_f32_e32 v19, v27, v27
	v_fmac_f32_e32 v19, v26, v26
	v_add_f32_e32 v18, v19, v18
	v_add_f32_e32 v30, v30, v18
	ds_bpermute_b32 v31, v178, v30
	v_lshl_add_u64 v[28:29], v[66:67], 0, v[160:161]
	v_lshl_add_u64 v[60:61], v[68:69], 1, s[24:25]
	v_lshl_add_u64 v[16:17], v[28:29], 2, s[48:49]
	global_store_dwordx4 v[60:61], v[56:59], off
	global_store_dwordx4 v[16:17], v[20:23], off nt
	global_store_dwordx4 v[16:17], v[24:27], off offset:16 nt
	s_waitcnt lgkmcnt(0)
	v_add_f32_e32 v16, v30, v31
	ds_bpermute_b32 v17, v179, v16
	v_cvt_pk_bf16_f32 v19, v22, v23
	v_lshl_add_u64 v[22:23], v[28:29], 1, s[24:25]
	v_cvt_pk_bf16_f32 v18, v20, v21
	v_cvt_pk_bf16_f32 v20, v24, v25
	v_cvt_pk_bf16_f32 v21, v26, v27
	global_store_dwordx4 v[22:23], v[18:21], off
	s_and_saveexec_b64 s[0:1], vcc
	s_cbranch_execz .LBB0_474
	v_lshl_add_u64 v[18:19], v[80:81], 2, s[10:11]
	s_waitcnt lgkmcnt(0)
	v_add_f32_e32 v16, v16, v17
	global_atomic_add_f32 v[18:19], v16, off
.LBB0_474:
	s_or_b64 exec, exec, s[0:1]
	s_waitcnt vmcnt(12)
	v_mov_b64_e32 v[40:41], v[228:229]
	v_mov_b64_e32 v[42:43], v[230:231]
	v_mov_b64_e32 v[44:45], v[232:233]
	v_mov_b64_e32 v[46:47], v[234:235]
	v_mov_b64_e32 v[32:33], v[236:237]
	v_mov_b64_e32 v[34:35], v[238:239]
	v_mov_b64_e32 v[36:37], v[240:241]
	v_mov_b64_e32 v[38:39], v[242:243]
	v_lshlrev_b64 v[20:21], 10, v[64:65]
	v_lshl_add_u64 v[22:23], v[20:21], 0, v[162:163]
	v_pk_add_f32 v[14:15], v[14:15], v[46:47]
	v_pk_add_f32 v[12:13], v[12:13], v[44:45]
	s_waitcnt lgkmcnt(0)
	v_lshl_add_u64 v[16:17], v[22:23], 2, s[48:49]
	v_pk_add_f32 v[10:11], v[10:11], v[42:43]
	v_pk_add_f32 v[8:9], v[8:9], v[40:41]
	global_store_dwordx4 v[16:17], v[12:15], off nt
	global_store_dwordx4 v[16:17], v[8:11], off offset:16 nt
	v_cvt_pk_bf16_f32 v16, v12, v13
	v_cvt_pk_bf16_f32 v18, v8, v9
	v_pk_add_f32 v[6:7], v[6:7], v[38:39]
	v_mul_f32_e32 v13, v13, v13
	v_fmac_f32_e32 v13, v12, v12
	v_mul_f32_e32 v12, v15, v15
	v_fmac_f32_e32 v12, v14, v14
	v_mul_f32_e32 v9, v9, v9
	v_add_f32_e32 v12, v13, v12
	v_fmac_f32_e32 v9, v8, v8
	v_add_f32_e32 v8, v12, v9
	v_mul_f32_e32 v9, v11, v11
	v_pk_add_f32 v[4:5], v[4:5], v[36:37]
	v_cvt_pk_bf16_f32 v19, v10, v11
	v_fmac_f32_e32 v9, v10, v10
	v_pk_add_f32 v[10:11], v[2:3], v[34:35]
	v_mul_f32_e32 v2, v5, v5
	v_mul_f32_e32 v3, v7, v7
	v_cvt_pk_bf16_f32 v17, v14, v15
	v_add_f32_e32 v14, v9, v8
	v_pk_add_f32 v[8:9], v[0:1], v[32:33]
	v_fmac_f32_e32 v2, v4, v4
	v_fmac_f32_e32 v3, v6, v6
	v_add_f32_e32 v2, v2, v3
	v_mul_f32_e32 v3, v9, v9
	v_fmac_f32_e32 v3, v8, v8
	v_add_f32_e32 v2, v2, v3
	v_mul_f32_e32 v3, v11, v11
	v_fmac_f32_e32 v3, v10, v10
	v_add_f32_e32 v2, v3, v2
	v_add_f32_e32 v14, v14, v2
	ds_bpermute_b32 v15, v178, v14
	v_lshl_add_u64 v[12:13], v[20:21], 0, v[160:161]
	v_lshl_add_u64 v[22:23], v[22:23], 1, s[24:25]
	v_lshl_add_u64 v[0:1], v[12:13], 2, s[48:49]
	global_store_dwordx4 v[22:23], v[16:19], off
	global_store_dwordx4 v[0:1], v[4:7], off nt
	global_store_dwordx4 v[0:1], v[8:11], off offset:16 nt
	s_waitcnt lgkmcnt(0)
	v_add_f32_e32 v0, v14, v15
	ds_bpermute_b32 v1, v179, v0
	v_cvt_pk_bf16_f32 v3, v6, v7
	v_lshl_add_u64 v[6:7], v[12:13], 1, s[24:25]
	v_cvt_pk_bf16_f32 v2, v4, v5
	v_cvt_pk_bf16_f32 v4, v8, v9
	v_cvt_pk_bf16_f32 v5, v10, v11
	global_store_dwordx4 v[6:7], v[2:5], off
	s_and_saveexec_b64 s[0:1], vcc
	s_cbranch_execz .LBB0_476
	v_lshl_add_u64 v[2:3], v[64:65], 2, s[10:11]
	s_waitcnt lgkmcnt(0)
	v_add_f32_e32 v0, v0, v1
	global_atomic_add_f32 v[2:3], v0, off

; #define EPI_IT_ROW(it) EPI_ROW((it) >> 2, (it) & 3)
; #define EPI_PACK8(v0, v1) (u32x4){pk2((v0)[0], (v0)[1]), pk2((v0)[2], (v0)[3]), pk2((v1)[0], (v1)[1]), pk2((v1)[2], (v1)[3])}
;     __device__ __forceinline__ void operator()(AccRef acc, const Unit& u, int wr, int wc, int fr, int fq) const {
;     ...
;         f32x4 xc[2][2], xn[2][2];
; #pragma unroll
;         for (int bj = 0; bj < 2; ++bj) { const size_t p = (size_t)EPI_IT_ROW(0) * DM + EPI_COL(bj); xc[bj][0] = *(const f32x4*)(xin + p); xc[bj][1] = *(const f32x4*)(xin + p + 4); }
; #pragma unroll
;         for (int it = 0; it < 8; ++it) { const int ai = it >> 2, m = it & 3, row = EPI_IT_ROW(it);
;             if (it + 1 < 8) {
; #pragma unroll
;                 for (int bj = 0; bj < 2; ++bj) { const size_t p = (size_t)EPI_IT_ROW(it + 1) * DM + EPI_COL(bj); xn[bj][0] = *(const f32x4*)(xin + p); xn[bj][1] = *(const f32x4*)(xin + p + 4); } }
;             float q = 0.f;
; #pragma unroll
;             for (int bj = 0; bj < 2; ++bj) { const size_t p = (size_t)row * DM + EPI_COL(bj);
;                 const f32x4 x0 = xc[bj][0] + acc[ai][bj][m][0], x1 = xc[bj][1] + acc[ai][bj][m][1];
;                 __builtin_nontemporal_store(x0, (f32x4*)(xout + p)); __builtin_nontemporal_store(x1, (f32x4*)(xout + p + 4));
;                 *(u32x4*)(xb + p) = EPI_PACK8(x0, x1);
;                 q += EPI_SQ8(x0, x1); }
;             q += __shfl_xor(q, 16); q += __shfl_xor(q, 32);
;             if (fq == 0) atomicAdd(ssout + row, q);
.LBB0_795:
	s_lshl_b32 s0, s74, 8
	v_mov_b32_e32 v128, v180
	v_mov_b32_e32 v186, v177
	s_add_i32 s0, s0, s56
	v_and_b32_e32 v202, 64, v185
	v_add_u32_e32 v164, s0, v128
	s_lshl_b32 s0, s73, 8
	s_or_b32 s0, s0, s57
	v_ashrrev_i32_e32 v165, 31, v164
	v_lshl_add_u32 v162, v186, 3, s0
	v_lshlrev_b64 v[128:129], 12, v[164:165]
	v_ashrrev_i32_e32 v163, 31, v162
	v_add_u32_e32 v160, 0x80, v162
	v_lshl_add_u64 v[128:129], s[48:49], 0, v[128:129]
	v_lshlrev_b64 v[130:131], 2, v[162:163]
	v_ashrrev_i32_e32 v161, 31, v160
	v_lshl_add_u64 v[178:179], v[128:129], 0, v[130:131]
	v_lshlrev_b64 v[132:133], 2, v[160:161]
	global_load_dwordx4 v[170:173], v[178:179], off offset:16
	global_load_dwordx4 v[188:191], v[178:179], off
	v_lshl_add_u64 v[200:201], v[128:129], 0, v[132:133]
	global_load_dwordx4 v[192:195], v[200:201], off
	global_load_dwordx4 v[196:199], v[200:201], off offset:16
	v_add_u32_e32 v166, 16, v164
	v_ashrrev_i32_e32 v167, 31, v166
	v_lshlrev_b64 v[128:129], 12, v[166:167]
	v_lshl_add_u64 v[128:129], s[48:49], 0, v[128:129]
	v_lshl_add_u64 v[174:175], v[128:129], 0, v[130:131]
	v_lshl_add_u64 v[168:169], v[128:129], 0, v[132:133]
	global_load_dwordx4 v[136:139], v[174:175], off offset:16
	global_load_dwordx4 v[140:143], v[174:175], off
	global_load_dwordx4 v[128:131], v[168:169], off offset:16
	global_load_dwordx4 v[132:135], v[168:169], off
	v_add_u32_e32 v244, 32, v164
	v_ashrrev_i32_e32 v245, 31, v244
	v_lshlrev_b64 v[246:247], 12, v[244:245]
	v_lshl_add_u64 v[246:247], s[48:49], 0, v[246:247]
	v_lshl_add_u64 v[248:249], v[162:163], 2, v[246:247]
	v_lshl_add_u64 v[250:251], v[160:161], 2, v[246:247]
	global_load_dwordx4 v[206:209], v[248:249], off offset:16
	global_load_dwordx4 v[210:213], v[248:249], off
	global_load_dwordx4 v[214:217], v[250:251], off offset:16
	global_load_dwordx4 v[218:221], v[250:251], off
	v_add_u32_e32 v244, 48, v164
	v_ashrrev_i32_e32 v245, 31, v244
	v_lshlrev_b64 v[246:247], 12, v[244:245]
	v_lshl_add_u64 v[246:247], s[48:49], 0, v[246:247]
	v_lshl_add_u64 v[248:249], v[162:163], 2, v[246:247]
	v_lshl_add_u64 v[250:251], v[160:161], 2, v[246:247]
	global_load_dwordx4 v[228:231], v[248:249], off offset:16
	global_load_dwordx4 v[232:235], v[248:249], off
	global_load_dwordx4 v[236:239], v[250:251], off offset:16
	global_load_dwordx4 v[240:243], v[250:251], off
	v_xor_b32_e32 v187, 16, v185
	v_add_u32_e32 v202, 64, v202
	v_cmp_lt_i32_e64 s[0:1], v187, v202
	v_cmp_eq_u32_e32 vcc, 0, v186
	v_xor_b32_e32 v203, 32, v185
	v_cndmask_b32_e64 v186, v185, v187, s[0:1]
	v_lshlrev_b32_e32 v186, 2, v186
	v_cmp_lt_i32_e64 s[0:1], v203, v202
	s_waitcnt vmcnt(8)
	v_pk_add_f32 v[122:123], v[122:123], v[172:173]
	v_pk_add_f32 v[126:127], v[126:127], v[190:191]
	v_pk_add_f32 v[124:125], v[124:125], v[188:189]
	v_pk_add_f32 v[118:119], v[118:119], v[194:195]
	v_pk_add_f32 v[116:117], v[116:117], v[192:193]
	v_pk_add_f32 v[120:121], v[120:121], v[170:171]
	v_pk_add_f32 v[170:171], v[112:113], v[196:197]
	global_store_dwordx4 v[178:179], v[124:127], off nt
	global_store_dwordx4 v[178:179], v[120:123], off offset:16 nt
	v_cvt_pk_bf16_f32 v112, v124, v125
	v_cvt_pk_bf16_f32 v113, v126, v127
	v_mul_f32_e32 v178, v117, v117
	v_mul_f32_e32 v125, v125, v125
	v_mul_f32_e32 v127, v127, v127
	v_mul_f32_e32 v179, v119, v119
	v_pk_add_f32 v[172:173], v[114:115], v[198:199]
	v_cvt_pk_bf16_f32 v114, v120, v121
	v_cvt_pk_bf16_f32 v115, v122, v123
	v_mul_f32_e32 v121, v121, v121
	v_mul_f32_e32 v123, v123, v123
	v_mul_f32_e32 v189, v171, v171
	v_fmac_f32_e32 v125, v124, v124
	v_fmac_f32_e32 v127, v126, v126
	v_fmac_f32_e32 v178, v116, v116
	v_fmac_f32_e32 v179, v118, v118
	v_mul_f32_e32 v190, v173, v173
	v_fmac_f32_e32 v121, v120, v120
	v_fmac_f32_e32 v123, v122, v122
	v_fmac_f32_e32 v189, v170, v170
	v_add_f32_e32 v120, v125, v127
	v_add_f32_e32 v122, v178, v179
	v_fmac_f32_e32 v190, v172, v172
	v_add_f32_e32 v120, v120, v121
	v_add_f32_e32 v121, v122, v189
	v_add_f32_e32 v120, v123, v120
	v_add_f32_e32 v121, v190, v121
	v_add_f32_e32 v120, v120, v121
	ds_bpermute_b32 v121, v186, v120
	v_cndmask_b32_e64 v187, v185, v203, s[0:1]
	v_lshlrev_b64 v[202:203], 10, v[164:165]
	v_lshl_add_u64 v[204:205], v[202:203], 0, v[162:163]
	v_lshl_add_u64 v[204:205], v[204:205], 1, s[30:31]
	global_store_dwordx4 v[204:205], v[112:115], off
	global_store_dwordx4 v[200:201], v[116:119], off nt
	global_store_dwordx4 v[200:201], v[170:173], off offset:16 nt
	s_waitcnt lgkmcnt(0)
	v_add_f32_e32 v112, v120, v121
	v_lshlrev_b32_e32 v187, 2, v187
	ds_bpermute_b32 v113, v187, v112
	v_lshl_add_u64 v[202:203], v[202:203], 0, v[160:161]
	v_lshl_add_u64 v[114:115], v[202:203], 1, s[30:31]
	v_cvt_pk_bf16_f32 v188, v116, v117
	v_cvt_pk_bf16_f32 v189, v118, v119
	v_cvt_pk_bf16_f32 v190, v170, v171
	v_cvt_pk_bf16_f32 v191, v172, v173
	global_store_dwordx4 v[114:115], v[188:191], off
	s_and_saveexec_b64 s[0:1], vcc
	s_cbranch_execz .LBB0_797
	v_lshl_add_u64 v[114:115], v[164:165], 2, s[12:13]
	s_waitcnt lgkmcnt(0)
	v_add_f32_e32 v112, v112, v113
	global_atomic_add_f32 v[114:115], v112, off
; #define EPI_IT_ROW(it) EPI_ROW((it) >> 2, (it) & 3)
; #define EPI_PACK8(v0, v1) (u32x4){pk2((v0)[0], (v0)[1]), pk2((v0)[2], (v0)[3]), pk2((v1)[0], (v1)[1]), pk2((v1)[2], (v1)[3])}
;     __device__ __forceinline__ void operator()(AccRef acc, const Unit& u, int wr, int wc, int fr, int fq) const {
;     ...
;         for (int it = 0; it < 8; ++it) { const int ai = it >> 2, m = it & 3, row = EPI_IT_ROW(it);
;             if (it + 1 < 8) {
; #pragma unroll
;                 for (int bj = 0; bj < 2; ++bj) { const size_t p = (size_t)EPI_IT_ROW(it + 1) * DM + EPI_COL(bj); xn[bj][0] = *(const f32x4*)(xin + p); xn[bj][1] = *(const f32x4*)(xin + p + 4); } }
;             float q = 0.f;
; #pragma unroll
;             for (int bj = 0; bj < 2; ++bj) { const size_t p = (size_t)row * DM + EPI_COL(bj);
;                 const f32x4 x0 = xc[bj][0] + acc[ai][bj][m][0], x1 = xc[bj][1] + acc[ai][bj][m][1];
;                 __builtin_nontemporal_store(x0, (f32x4*)(xout + p)); __builtin_nontemporal_store(x1, (f32x4*)(xout + p + 4));
;                 *(u32x4*)(xb + p) = EPI_PACK8(x0, x1);
;                 q += EPI_SQ8(x0, x1); }
;             q += __shfl_xor(q, 16); q += __shfl_xor(q, 32);
;             if (fq == 0) atomicAdd(ssout + row, q);
; #pragma unroll
;             for (int bj = 0; bj < 2; ++bj) { xc[bj][0] = xn[bj][0]; xc[bj][1] = xn[bj][1]; } }
.LBB0_797:
	s_or_b64 exec, exec, s[0:1]
	v_add_u32_e32 v170, 32, v164
	v_ashrrev_i32_e32 v171, 31, v170
	s_waitcnt lgkmcnt(0)
	v_lshlrev_b64 v[112:113], 12, v[170:171]
	v_lshl_add_u64 v[112:113], s[48:49], 0, v[112:113]
	v_lshl_add_u64 v[178:179], v[162:163], 2, v[112:113]
	v_lshl_add_u64 v[172:173], v[160:161], 2, v[112:113]
	v_pk_add_f32 v[110:111], v[110:111], v[142:143]
	v_pk_add_f32 v[108:109], v[108:109], v[140:141]
	v_pk_add_f32 v[106:107], v[106:107], v[138:139]
	v_pk_add_f32 v[104:105], v[104:105], v[136:137]
	global_store_dwordx4 v[174:175], v[108:111], off nt
	global_store_dwordx4 v[174:175], v[104:107], off offset:16 nt
	v_cvt_pk_bf16_f32 v136, v108, v109
	v_cvt_pk_bf16_f32 v138, v104, v105
	v_pk_add_f32 v[102:103], v[102:103], v[134:135]
	v_mul_f32_e32 v109, v109, v109
	v_fmac_f32_e32 v109, v108, v108
	v_mul_f32_e32 v108, v111, v111
	v_fmac_f32_e32 v108, v110, v110
	v_mul_f32_e32 v105, v105, v105
	v_add_f32_e32 v108, v109, v108
	v_fmac_f32_e32 v105, v104, v104
	v_add_f32_e32 v104, v108, v105
	v_mul_f32_e32 v105, v107, v107
	v_fmac_f32_e32 v105, v106, v106
	v_pk_add_f32 v[100:101], v[100:101], v[132:133]
	v_cvt_pk_bf16_f32 v137, v110, v111
	v_add_f32_e32 v110, v105, v104
	v_pk_add_f32 v[104:105], v[96:97], v[128:129]
	v_mul_f32_e32 v96, v101, v101
	v_mul_f32_e32 v97, v103, v103
	v_fmac_f32_e32 v96, v100, v100
	v_fmac_f32_e32 v97, v102, v102
	v_add_f32_e32 v96, v96, v97
	v_mul_f32_e32 v97, v105, v105
	v_cvt_pk_bf16_f32 v139, v106, v107
	v_pk_add_f32 v[106:107], v[98:99], v[130:131]
	v_fmac_f32_e32 v97, v104, v104
	v_add_f32_e32 v96, v96, v97
	v_mul_f32_e32 v97, v107, v107
	v_fmac_f32_e32 v97, v106, v106
	v_add_f32_e32 v96, v97, v96
	v_add_f32_e32 v96, v110, v96
	ds_bpermute_b32 v97, v186, v96
	v_lshlrev_b64 v[188:189], 10, v[166:167]
	v_lshl_add_u64 v[190:191], v[188:189], 0, v[162:163]
	v_lshl_add_u64 v[140:141], v[190:191], 1, s[30:31]
	v_lshl_add_u64 v[108:109], v[188:189], 0, v[160:161]
	s_waitcnt lgkmcnt(0)
	v_add_f32_e32 v96, v96, v97
	ds_bpermute_b32 v97, v187, v96
	global_store_dwordx4 v[140:141], v[136:139], off
	global_store_dwordx4 v[168:169], v[100:103], off nt
	global_store_dwordx4 v[168:169], v[104:107], off offset:16 nt
	v_cvt_pk_bf16_f32 v99, v102, v103
	v_cvt_pk_bf16_f32 v98, v100, v101
	s_nop 0
	v_lshl_add_u64 v[102:103], v[108:109], 1, s[30:31]
	v_cvt_pk_bf16_f32 v100, v104, v105
	v_cvt_pk_bf16_f32 v101, v106, v107
	global_store_dwordx4 v[102:103], v[98:101], off
	s_and_saveexec_b64 s[0:1], vcc
	s_cbranch_execz .LBB0_799
	v_lshl_add_u64 v[98:99], v[166:167], 2, s[12:13]
	s_waitcnt lgkmcnt(0)
	v_add_f32_e32 v96, v96, v97
	global_atomic_add_f32 v[98:99], v96, off
.LBB0_799:
	s_or_b64 exec, exec, s[0:1]
	s_waitcnt vmcnt(16)
	v_mov_b64_e32 v[120:121], v[206:207]
	v_mov_b64_e32 v[122:123], v[208:209]
	v_mov_b64_e32 v[124:125], v[210:211]
	v_mov_b64_e32 v[126:127], v[212:213]
	v_mov_b64_e32 v[112:113], v[214:215]
	v_mov_b64_e32 v[114:115], v[216:217]
	v_mov_b64_e32 v[116:117], v[218:219]
	v_mov_b64_e32 v[118:119], v[220:221]
	v_add_u32_e32 v244, 128, v164
	v_ashrrev_i32_e32 v245, 31, v244
	v_lshlrev_b64 v[246:247], 12, v[244:245]
	v_lshl_add_u64 v[246:247], s[48:49], 0, v[246:247]
	v_lshl_add_u64 v[248:249], v[162:163], 2, v[246:247]
	v_lshl_add_u64 v[250:251], v[160:161], 2, v[246:247]
	global_load_dwordx4 v[206:209], v[248:249], off offset:16
	global_load_dwordx4 v[210:213], v[248:249], off
	global_load_dwordx4 v[214:217], v[250:251], off offset:16
	global_load_dwordx4 v[218:221], v[250:251], off
	v_add_u32_e32 v128, 48, v164
	v_ashrrev_i32_e32 v129, 31, v128
	s_waitcnt lgkmcnt(0)
	v_lshlrev_b64 v[96:97], 12, v[128:129]
	v_lshl_add_u64 v[96:97], s[48:49], 0, v[96:97]
	v_lshl_add_u64 v[132:133], v[162:163], 2, v[96:97]
	v_lshl_add_u64 v[130:131], v[160:161], 2, v[96:97]
	v_pk_add_f32 v[94:95], v[94:95], v[126:127]
	v_pk_add_f32 v[92:93], v[92:93], v[124:125]
	v_pk_add_f32 v[90:91], v[90:91], v[122:123]
	v_pk_add_f32 v[88:89], v[88:89], v[120:121]
	global_store_dwordx4 v[178:179], v[92:95], off nt
	global_store_dwordx4 v[178:179], v[88:91], off offset:16 nt
	v_cvt_pk_bf16_f32 v120, v92, v93
	v_cvt_pk_bf16_f32 v122, v88, v89
	v_pk_add_f32 v[86:87], v[86:87], v[118:119]
	v_mul_f32_e32 v93, v93, v93
	v_fmac_f32_e32 v93, v92, v92
	v_mul_f32_e32 v92, v95, v95
	v_fmac_f32_e32 v92, v94, v94
	v_mul_f32_e32 v89, v89, v89
	v_add_f32_e32 v92, v93, v92
	v_fmac_f32_e32 v89, v88, v88
	v_add_f32_e32 v88, v92, v89
	v_mul_f32_e32 v89, v91, v91
	v_fmac_f32_e32 v89, v90, v90
	v_pk_add_f32 v[84:85], v[84:85], v[116:117]
	v_cvt_pk_bf16_f32 v121, v94, v95
	v_add_f32_e32 v94, v89, v88
	v_pk_add_f32 v[88:89], v[80:81], v[112:113]
	v_mul_f32_e32 v80, v85, v85
	v_mul_f32_e32 v81, v87, v87
	v_fmac_f32_e32 v80, v84, v84
	v_fmac_f32_e32 v81, v86, v86
	v_add_f32_e32 v80, v80, v81
	v_mul_f32_e32 v81, v89, v89
	v_cvt_pk_bf16_f32 v123, v90, v91
	v_pk_add_f32 v[90:91], v[82:83], v[114:115]
	v_fmac_f32_e32 v81, v88, v88
	v_add_f32_e32 v80, v80, v81
	v_mul_f32_e32 v81, v91, v91
	v_fmac_f32_e32 v81, v90, v90
	v_add_f32_e32 v80, v81, v80
	v_add_f32_e32 v80, v94, v80
	ds_bpermute_b32 v81, v186, v80
	v_lshlrev_b64 v[134:135], 10, v[170:171]
	v_lshl_add_u64 v[136:137], v[134:135], 0, v[162:163]
	v_lshl_add_u64 v[124:125], v[136:137], 1, s[30:31]
	v_lshl_add_u64 v[92:93], v[134:135], 0, v[160:161]
	s_waitcnt lgkmcnt(0)
	v_add_f32_e32 v80, v80, v81
	ds_bpermute_b32 v81, v187, v80
	global_store_dwordx4 v[124:125], v[120:123], off
	global_store_dwordx4 v[172:173], v[84:87], off nt
	global_store_dwordx4 v[172:173], v[88:91], off offset:16 nt
	v_cvt_pk_bf16_f32 v83, v86, v87
	v_cvt_pk_bf16_f32 v82, v84, v85
	s_nop 0
	v_lshl_add_u64 v[86:87], v[92:93], 1, s[30:31]
	v_cvt_pk_bf16_f32 v84, v88, v89
	v_cvt_pk_bf16_f32 v85, v90, v91
	global_store_dwordx4 v[86:87], v[82:85], off
	s_and_saveexec_b64 s[0:1], vcc
	s_cbranch_execz .LBB0_801
	v_lshl_add_u64 v[82:83], v[170:171], 2, s[12:13]
	s_waitcnt lgkmcnt(0)
	v_add_f32_e32 v80, v80, v81
	global_atomic_add_f32 v[82:83], v80, off
; #define EPI_IT_ROW(it) EPI_ROW((it) >> 2, (it) & 3)
; #define EPI_PACK8(v0, v1) (u32x4){pk2((v0)[0], (v0)[1]), pk2((v0)[2], (v0)[3]), pk2((v1)[0], (v1)[1]), pk2((v1)[2], (v1)[3])}
;     __device__ __forceinline__ void operator()(AccRef acc, const Unit& u, int wr, int wc, int fr, int fq) const {
;     ...
;         for (int it = 0; it < 8; ++it) { const int ai = it >> 2, m = it & 3, row = EPI_IT_ROW(it);
;             if (it + 1 < 8) {
; #pragma unroll
;                 for (int bj = 0; bj < 2; ++bj) { const size_t p = (size_t)EPI_IT_ROW(it + 1) * DM + EPI_COL(bj); xn[bj][0] = *(const f32x4*)(xin + p); xn[bj][1] = *(const f32x4*)(xin + p + 4); } }
;             float q = 0.f;
; #pragma unroll
;             for (int bj = 0; bj < 2; ++bj) { const size_t p = (size_t)row * DM + EPI_COL(bj);
;                 const f32x4 x0 = xc[bj][0] + acc[ai][bj][m][0], x1 = xc[bj][1] + acc[ai][bj][m][1];
;                 __builtin_nontemporal_store(x0, (f32x4*)(xout + p)); __builtin_nontemporal_store(x1, (f32x4*)(xout + p + 4));
;                 *(u32x4*)(xb + p) = EPI_PACK8(x0, x1);
;                 q += EPI_SQ8(x0, x1); }
;             q += __shfl_xor(q, 16); q += __shfl_xor(q, 32);
;             if (fq == 0) atomicAdd(ssout + row, q);
; #pragma unroll
;             for (int bj = 0; bj < 2; ++bj) { xc[bj][0] = xn[bj][0]; xc[bj][1] = xn[bj][1]; } }
.LBB0_801:
	s_or_b64 exec, exec, s[0:1]
	s_waitcnt vmcnt(22)
	v_mov_b64_e32 v[104:105], v[228:229]
	v_mov_b64_e32 v[106:107], v[230:231]
	v_mov_b64_e32 v[108:109], v[232:233]
	v_mov_b64_e32 v[110:111], v[234:235]
	v_mov_b64_e32 v[96:97], v[236:237]
	v_mov_b64_e32 v[98:99], v[238:239]
	v_mov_b64_e32 v[100:101], v[240:241]
	v_mov_b64_e32 v[102:103], v[242:243]
	v_add_u32_e32 v244, 144, v164
	v_ashrrev_i32_e32 v245, 31, v244
	v_lshlrev_b64 v[246:247], 12, v[244:245]
	v_lshl_add_u64 v[246:247], s[48:49], 0, v[246:247]
	v_lshl_add_u64 v[248:249], v[162:163], 2, v[246:247]
	v_lshl_add_u64 v[250:251], v[160:161], 2, v[246:247]
	global_load_dwordx4 v[228:231], v[248:249], off offset:16
	global_load_dwordx4 v[232:235], v[248:249], off
	global_load_dwordx4 v[236:239], v[250:251], off offset:16
	global_load_dwordx4 v[240:243], v[250:251], off
	v_add_u32_e32 v112, 0x80, v164
	v_ashrrev_i32_e32 v113, 31, v112
	s_waitcnt lgkmcnt(0)
	v_lshlrev_b64 v[80:81], 12, v[112:113]
	v_lshl_add_u64 v[80:81], s[48:49], 0, v[80:81]
	v_lshl_add_u64 v[116:117], v[162:163], 2, v[80:81]
	v_lshl_add_u64 v[114:115], v[160:161], 2, v[80:81]
	v_pk_add_f32 v[78:79], v[78:79], v[110:111]
	v_pk_add_f32 v[76:77], v[76:77], v[108:109]
	v_pk_add_f32 v[74:75], v[74:75], v[106:107]
	v_pk_add_f32 v[72:73], v[72:73], v[104:105]
	global_store_dwordx4 v[132:133], v[76:79], off nt
	global_store_dwordx4 v[132:133], v[72:75], off offset:16 nt
	v_cvt_pk_bf16_f32 v104, v76, v77
	v_cvt_pk_bf16_f32 v106, v72, v73
	v_pk_add_f32 v[70:71], v[70:71], v[102:103]
	v_mul_f32_e32 v77, v77, v77
	v_fmac_f32_e32 v77, v76, v76
	v_mul_f32_e32 v76, v79, v79
	v_fmac_f32_e32 v76, v78, v78
	v_mul_f32_e32 v73, v73, v73
	v_add_f32_e32 v76, v77, v76
	v_fmac_f32_e32 v73, v72, v72
	v_add_f32_e32 v72, v76, v73
	v_mul_f32_e32 v73, v75, v75
	v_fmac_f32_e32 v73, v74, v74
	v_pk_add_f32 v[68:69], v[68:69], v[100:101]
	v_cvt_pk_bf16_f32 v105, v78, v79
	v_add_f32_e32 v78, v73, v72
	v_pk_add_f32 v[72:73], v[64:65], v[96:97]
	v_mul_f32_e32 v64, v69, v69
	v_mul_f32_e32 v65, v71, v71
	v_fmac_f32_e32 v64, v68, v68
	v_fmac_f32_e32 v65, v70, v70
	v_add_f32_e32 v64, v64, v65
	v_mul_f32_e32 v65, v73, v73
	v_cvt_pk_bf16_f32 v107, v74, v75
	v_pk_add_f32 v[74:75], v[66:67], v[98:99]
	v_fmac_f32_e32 v65, v72, v72
	v_add_f32_e32 v64, v64, v65
	v_mul_f32_e32 v65, v75, v75
	v_fmac_f32_e32 v65, v74, v74
	v_add_f32_e32 v64, v65, v64
	v_add_f32_e32 v64, v78, v64
	ds_bpermute_b32 v65, v186, v64
	v_lshlrev_b64 v[118:119], 10, v[128:129]
	v_lshl_add_u64 v[120:121], v[118:119], 0, v[162:163]
	v_lshl_add_u64 v[108:109], v[120:121], 1, s[30:31]
	v_lshl_add_u64 v[76:77], v[118:119], 0, v[160:161]
	s_waitcnt lgkmcnt(0)
	v_add_f32_e32 v64, v64, v65
	ds_bpermute_b32 v65, v187, v64
	global_store_dwordx4 v[108:109], v[104:107], off
	global_store_dwordx4 v[130:131], v[68:71], off nt
	global_store_dwordx4 v[130:131], v[72:75], off offset:16 nt
	v_cvt_pk_bf16_f32 v67, v70, v71
	v_cvt_pk_bf16_f32 v66, v68, v69
	s_nop 0
	v_lshl_add_u64 v[70:71], v[76:77], 1, s[30:31]
	v_cvt_pk_bf16_f32 v68, v72, v73
	v_cvt_pk_bf16_f32 v69, v74, v75
	global_store_dwordx4 v[70:71], v[66:69], off
	s_and_saveexec_b64 s[0:1], vcc
	s_cbranch_execz .LBB0_803
	v_lshl_add_u64 v[66:67], v[128:129], 2, s[12:13]
	s_waitcnt lgkmcnt(0)
	v_add_f32_e32 v64, v64, v65
	global_atomic_add_f32 v[66:67], v64, off
.LBB0_803:
	s_or_b64 exec, exec, s[0:1]
	s_waitcnt vmcnt(16)
	v_mov_b64_e32 v[88:89], v[206:207]
	v_mov_b64_e32 v[90:91], v[208:209]
	v_mov_b64_e32 v[92:93], v[210:211]
	v_mov_b64_e32 v[94:95], v[212:213]
	v_mov_b64_e32 v[80:81], v[214:215]
	v_mov_b64_e32 v[82:83], v[216:217]
	v_mov_b64_e32 v[84:85], v[218:219]
	v_mov_b64_e32 v[86:87], v[220:221]
	v_add_u32_e32 v244, 160, v164
	v_ashrrev_i32_e32 v245, 31, v244
	v_lshlrev_b64 v[246:247], 12, v[244:245]
	v_lshl_add_u64 v[246:247], s[48:49], 0, v[246:247]
	v_lshl_add_u64 v[248:249], v[162:163], 2, v[246:247]
	v_lshl_add_u64 v[250:251], v[160:161], 2, v[246:247]
	global_load_dwordx4 v[206:209], v[248:249], off offset:16
	global_load_dwordx4 v[210:213], v[248:249], off
	global_load_dwordx4 v[214:217], v[250:251], off offset:16
	global_load_dwordx4 v[218:221], v[250:251], off
	v_add_u32_e32 v96, 0x90, v164
	v_ashrrev_i32_e32 v97, 31, v96
	s_waitcnt lgkmcnt(0)
	v_lshlrev_b64 v[64:65], 12, v[96:97]
	v_lshl_add_u64 v[64:65], s[48:49], 0, v[64:65]
	v_lshl_add_u64 v[100:101], v[162:163], 2, v[64:65]
	v_lshl_add_u64 v[98:99], v[160:161], 2, v[64:65]
	v_pk_add_f32 v[62:63], v[62:63], v[94:95]
	v_pk_add_f32 v[60:61], v[60:61], v[92:93]
	v_pk_add_f32 v[58:59], v[58:59], v[90:91]
	v_pk_add_f32 v[56:57], v[56:57], v[88:89]
	global_store_dwordx4 v[116:117], v[60:63], off nt
	global_store_dwordx4 v[116:117], v[56:59], off offset:16 nt
	v_cvt_pk_bf16_f32 v88, v60, v61
	v_cvt_pk_bf16_f32 v90, v56, v57
	v_pk_add_f32 v[54:55], v[54:55], v[86:87]
	v_mul_f32_e32 v61, v61, v61
	v_fmac_f32_e32 v61, v60, v60
	v_mul_f32_e32 v60, v63, v63
	v_fmac_f32_e32 v60, v62, v62
	v_mul_f32_e32 v57, v57, v57
	v_add_f32_e32 v60, v61, v60
	v_fmac_f32_e32 v57, v56, v56
	v_add_f32_e32 v56, v60, v57
	v_mul_f32_e32 v57, v59, v59
	v_fmac_f32_e32 v57, v58, v58
	v_pk_add_f32 v[52:53], v[52:53], v[84:85]
	v_cvt_pk_bf16_f32 v89, v62, v63
	v_add_f32_e32 v62, v57, v56
	v_pk_add_f32 v[56:57], v[48:49], v[80:81]
	v_mul_f32_e32 v48, v53, v53
	v_mul_f32_e32 v49, v55, v55
	v_fmac_f32_e32 v48, v52, v52
	v_fmac_f32_e32 v49, v54, v54
	v_add_f32_e32 v48, v48, v49
	v_mul_f32_e32 v49, v57, v57
	v_cvt_pk_bf16_f32 v91, v58, v59
	v_pk_add_f32 v[58:59], v[50:51], v[82:83]
	v_fmac_f32_e32 v49, v56, v56
	v_add_f32_e32 v48, v48, v49
	v_mul_f32_e32 v49, v59, v59
	v_fmac_f32_e32 v49, v58, v58
	v_add_f32_e32 v48, v49, v48
	v_add_f32_e32 v48, v62, v48
	ds_bpermute_b32 v49, v186, v48
	v_lshlrev_b64 v[102:103], 10, v[112:113]
	v_lshl_add_u64 v[104:105], v[102:103], 0, v[162:163]
	v_lshl_add_u64 v[92:93], v[104:105], 1, s[30:31]
	v_lshl_add_u64 v[60:61], v[102:103], 0, v[160:161]
	s_waitcnt lgkmcnt(0)
	v_add_f32_e32 v48, v48, v49
	ds_bpermute_b32 v49, v187, v48
	global_store_dwordx4 v[92:93], v[88:91], off
	global_store_dwordx4 v[114:115], v[52:55], off nt
	global_store_dwordx4 v[114:115], v[56:59], off offset:16 nt
	v_cvt_pk_bf16_f32 v51, v54, v55
	v_cvt_pk_bf16_f32 v50, v52, v53
	s_nop 0
	v_lshl_add_u64 v[54:55], v[60:61], 1, s[30:31]
	v_cvt_pk_bf16_f32 v52, v56, v57
	v_cvt_pk_bf16_f32 v53, v58, v59
	global_store_dwordx4 v[54:55], v[50:53], off
	s_and_saveexec_b64 s[0:1], vcc
	s_cbranch_execz .LBB0_805
	v_lshl_add_u64 v[50:51], v[112:113], 2, s[12:13]
	s_waitcnt lgkmcnt(0)
	v_add_f32_e32 v48, v48, v49
	global_atomic_add_f32 v[50:51], v48, off
; #define EPI_IT_ROW(it) EPI_ROW((it) >> 2, (it) & 3)
; #define EPI_PACK8(v0, v1) (u32x4){pk2((v0)[0], (v0)[1]), pk2((v0)[2], (v0)[3]), pk2((v1)[0], (v1)[1]), pk2((v1)[2], (v1)[3])}
;     __device__ __forceinline__ void operator()(AccRef acc, const Unit& u, int wr, int wc, int fr, int fq) const {
;     ...
;         for (int it = 0; it < 8; ++it) { const int ai = it >> 2, m = it & 3, row = EPI_IT_ROW(it);
;             if (it + 1 < 8) {
; #pragma unroll
;                 for (int bj = 0; bj < 2; ++bj) { const size_t p = (size_t)EPI_IT_ROW(it + 1) * DM + EPI_COL(bj); xn[bj][0] = *(const f32x4*)(xin + p); xn[bj][1] = *(const f32x4*)(xin + p + 4); } }
;             float q = 0.f;
; #pragma unroll
;             for (int bj = 0; bj < 2; ++bj) { const size_t p = (size_t)row * DM + EPI_COL(bj);
;                 const f32x4 x0 = xc[bj][0] + acc[ai][bj][m][0], x1 = xc[bj][1] + acc[ai][bj][m][1];
;                 __builtin_nontemporal_store(x0, (f32x4*)(xout + p)); __builtin_nontemporal_store(x1, (f32x4*)(xout + p + 4));
;                 *(u32x4*)(xb + p) = EPI_PACK8(x0, x1);
;                 q += EPI_SQ8(x0, x1); }
;             q += __shfl_xor(q, 16); q += __shfl_xor(q, 32);
;             if (fq == 0) atomicAdd(ssout + row, q);
; #pragma unroll
;             for (int bj = 0; bj < 2; ++bj) { xc[bj][0] = xn[bj][0]; xc[bj][1] = xn[bj][1]; } }
.LBB0_805:
	s_or_b64 exec, exec, s[0:1]
	s_waitcnt vmcnt(16)
	v_mov_b64_e32 v[72:73], v[228:229]
	v_mov_b64_e32 v[74:75], v[230:231]
	v_mov_b64_e32 v[76:77], v[232:233]
	v_mov_b64_e32 v[78:79], v[234:235]
	v_mov_b64_e32 v[64:65], v[236:237]
	v_mov_b64_e32 v[66:67], v[238:239]
	v_mov_b64_e32 v[68:69], v[240:241]
	v_mov_b64_e32 v[70:71], v[242:243]
	v_add_u32_e32 v244, 176, v164
	v_ashrrev_i32_e32 v245, 31, v244
	v_lshlrev_b64 v[246:247], 12, v[244:245]
	v_lshl_add_u64 v[246:247], s[48:49], 0, v[246:247]
	v_lshl_add_u64 v[248:249], v[162:163], 2, v[246:247]
	v_lshl_add_u64 v[250:251], v[160:161], 2, v[246:247]
	global_load_dwordx4 v[228:231], v[248:249], off offset:16
	global_load_dwordx4 v[232:235], v[248:249], off
	global_load_dwordx4 v[236:239], v[250:251], off offset:16
	global_load_dwordx4 v[240:243], v[250:251], off
	v_add_u32_e32 v80, 0xa0, v164
	v_ashrrev_i32_e32 v81, 31, v80
	s_waitcnt lgkmcnt(0)
	v_lshlrev_b64 v[48:49], 12, v[80:81]
	v_lshl_add_u64 v[48:49], s[48:49], 0, v[48:49]
	v_lshl_add_u64 v[84:85], v[162:163], 2, v[48:49]
	v_lshl_add_u64 v[82:83], v[160:161], 2, v[48:49]
	v_pk_add_f32 v[46:47], v[46:47], v[78:79]
	v_pk_add_f32 v[44:45], v[44:45], v[76:77]
	v_pk_add_f32 v[42:43], v[42:43], v[74:75]
	v_pk_add_f32 v[40:41], v[40:41], v[72:73]
	global_store_dwordx4 v[100:101], v[44:47], off nt
	global_store_dwordx4 v[100:101], v[40:43], off offset:16 nt
	v_cvt_pk_bf16_f32 v72, v44, v45
	v_cvt_pk_bf16_f32 v74, v40, v41
	v_pk_add_f32 v[38:39], v[38:39], v[70:71]
	v_mul_f32_e32 v45, v45, v45
	v_fmac_f32_e32 v45, v44, v44
	v_mul_f32_e32 v44, v47, v47
	v_fmac_f32_e32 v44, v46, v46
	v_mul_f32_e32 v41, v41, v41
	v_add_f32_e32 v44, v45, v44
	v_fmac_f32_e32 v41, v40, v40
	v_add_f32_e32 v40, v44, v41
	v_mul_f32_e32 v41, v43, v43
	v_fmac_f32_e32 v41, v42, v42
	v_pk_add_f32 v[36:37], v[36:37], v[68:69]
	v_cvt_pk_bf16_f32 v73, v46, v47
	v_add_f32_e32 v46, v41, v40
	v_pk_add_f32 v[40:41], v[32:33], v[64:65]
	v_mul_f32_e32 v32, v37, v37
	v_mul_f32_e32 v33, v39, v39
	v_fmac_f32_e32 v32, v36, v36
	v_fmac_f32_e32 v33, v38, v38
	v_add_f32_e32 v32, v32, v33
	v_mul_f32_e32 v33, v41, v41
	v_cvt_pk_bf16_f32 v75, v42, v43
	v_pk_add_f32 v[42:43], v[34:35], v[66:67]
	v_fmac_f32_e32 v33, v40, v40
	v_add_f32_e32 v32, v32, v33
	v_mul_f32_e32 v33, v43, v43
	v_fmac_f32_e32 v33, v42, v42
	v_add_f32_e32 v32, v33, v32
	v_add_f32_e32 v32, v46, v32
	ds_bpermute_b32 v33, v186, v32
	v_lshlrev_b64 v[86:87], 10, v[96:97]
	v_lshl_add_u64 v[88:89], v[86:87], 0, v[162:163]
	v_lshl_add_u64 v[76:77], v[88:89], 1, s[30:31]
	v_lshl_add_u64 v[44:45], v[86:87], 0, v[160:161]
	s_waitcnt lgkmcnt(0)
	v_add_f32_e32 v32, v32, v33
	ds_bpermute_b32 v33, v187, v32
	global_store_dwordx4 v[76:77], v[72:75], off
	global_store_dwordx4 v[98:99], v[36:39], off nt
	global_store_dwordx4 v[98:99], v[40:43], off offset:16 nt
	v_cvt_pk_bf16_f32 v35, v38, v39
	v_cvt_pk_bf16_f32 v34, v36, v37
	s_nop 0
	v_lshl_add_u64 v[38:39], v[44:45], 1, s[30:31]
	v_cvt_pk_bf16_f32 v36, v40, v41
	v_cvt_pk_bf16_f32 v37, v42, v43
	global_store_dwordx4 v[38:39], v[34:37], off
	s_and_saveexec_b64 s[0:1], vcc
	s_cbranch_execz .LBB0_807
	v_lshl_add_u64 v[34:35], v[96:97], 2, s[12:13]
	s_waitcnt lgkmcnt(0)
	v_add_f32_e32 v32, v32, v33
	global_atomic_add_f32 v[34:35], v32, off
; #define EPI_IT_ROW(it) EPI_ROW((it) >> 2, (it) & 3)
; #define EPI_PACK8(v0, v1) (u32x4){pk2((v0)[0], (v0)[1]), pk2((v0)[2], (v0)[3]), pk2((v1)[0], (v1)[1]), pk2((v1)[2], (v1)[3])}
;     __device__ __forceinline__ void operator()(AccRef acc, const Unit& u, int wr, int wc, int fr, int fq) const {
;     ...
;         for (int it = 0; it < 8; ++it) { const int ai = it >> 2, m = it & 3, row = EPI_IT_ROW(it);
;             if (it + 1 < 8) {
; #pragma unroll
;                 for (int bj = 0; bj < 2; ++bj) { const size_t p = (size_t)EPI_IT_ROW(it + 1) * DM + EPI_COL(bj); xn[bj][0] = *(const f32x4*)(xin + p); xn[bj][1] = *(const f32x4*)(xin + p + 4); } }
;             float q = 0.f;
; #pragma unroll
;             for (int bj = 0; bj < 2; ++bj) { const size_t p = (size_t)row * DM + EPI_COL(bj);
;                 const f32x4 x0 = xc[bj][0] + acc[ai][bj][m][0], x1 = xc[bj][1] + acc[ai][bj][m][1];
;                 __builtin_nontemporal_store(x0, (f32x4*)(xout + p)); __builtin_nontemporal_store(x1, (f32x4*)(xout + p + 4));
;                 *(u32x4*)(xb + p) = EPI_PACK8(x0, x1);
;                 q += EPI_SQ8(x0, x1); }
;             q += __shfl_xor(q, 16); q += __shfl_xor(q, 32);
;             if (fq == 0) atomicAdd(ssout + row, q);
; #pragma unroll
;             for (int bj = 0; bj < 2; ++bj) { xc[bj][0] = xn[bj][0]; xc[bj][1] = xn[bj][1]; } }
.LBB0_807:
	s_or_b64 exec, exec, s[0:1]
	s_waitcnt vmcnt(16)
	v_mov_b64_e32 v[56:57], v[206:207]
	v_mov_b64_e32 v[58:59], v[208:209]
	v_mov_b64_e32 v[60:61], v[210:211]
	v_mov_b64_e32 v[62:63], v[212:213]
	v_mov_b64_e32 v[48:49], v[214:215]
	v_mov_b64_e32 v[50:51], v[216:217]
	v_mov_b64_e32 v[52:53], v[218:219]
	v_mov_b64_e32 v[54:55], v[220:221]
	v_add_u32_e32 v64, 0xb0, v164
	v_ashrrev_i32_e32 v65, 31, v64
	s_waitcnt lgkmcnt(0)
	v_lshlrev_b64 v[32:33], 12, v[64:65]
	v_lshl_add_u64 v[32:33], s[48:49], 0, v[32:33]
	v_lshl_add_u64 v[68:69], v[162:163], 2, v[32:33]
	v_lshl_add_u64 v[66:67], v[160:161], 2, v[32:33]
	v_pk_add_f32 v[30:31], v[30:31], v[62:63]
	v_pk_add_f32 v[28:29], v[28:29], v[60:61]
	v_pk_add_f32 v[26:27], v[26:27], v[58:59]
	v_pk_add_f32 v[24:25], v[24:25], v[56:57]
	global_store_dwordx4 v[84:85], v[28:31], off nt
	global_store_dwordx4 v[84:85], v[24:27], off offset:16 nt
	v_cvt_pk_bf16_f32 v56, v28, v29
	v_cvt_pk_bf16_f32 v58, v24, v25
	v_pk_add_f32 v[22:23], v[22:23], v[54:55]
	v_mul_f32_e32 v29, v29, v29
	v_fmac_f32_e32 v29, v28, v28
	v_mul_f32_e32 v28, v31, v31
	v_fmac_f32_e32 v28, v30, v30
	v_mul_f32_e32 v25, v25, v25
	v_add_f32_e32 v28, v29, v28
	v_fmac_f32_e32 v25, v24, v24
	v_add_f32_e32 v24, v28, v25
	v_mul_f32_e32 v25, v27, v27
	v_fmac_f32_e32 v25, v26, v26
	v_pk_add_f32 v[20:21], v[20:21], v[52:53]
	v_cvt_pk_bf16_f32 v57, v30, v31
	v_add_f32_e32 v30, v25, v24
	v_pk_add_f32 v[24:25], v[16:17], v[48:49]
	v_mul_f32_e32 v16, v21, v21
	v_mul_f32_e32 v17, v23, v23
	v_fmac_f32_e32 v16, v20, v20
	v_fmac_f32_e32 v17, v22, v22
	v_add_f32_e32 v16, v16, v17
	v_mul_f32_e32 v17, v25, v25
	v_cvt_pk_bf16_f32 v59, v26, v27
	v_pk_add_f32 v[26:27], v[18:19], v[50:51]
	v_fmac_f32_e32 v17, v24, v24
	v_add_f32_e32 v16, v16, v17
	v_mul_f32_e32 v17, v27, v27
	v_fmac_f32_e32 v17, v26, v26
	v_add_f32_e32 v16, v17, v16
	v_add_f32_e32 v16, v30, v16
	ds_bpermute_b32 v17, v186, v16
	v_lshlrev_b64 v[70:71], 10, v[80:81]
	v_lshl_add_u64 v[72:73], v[70:71], 0, v[162:163]
	v_lshl_add_u64 v[60:61], v[72:73], 1, s[30:31]
	v_lshl_add_u64 v[28:29], v[70:71], 0, v[160:161]
	s_waitcnt lgkmcnt(0)
	v_add_f32_e32 v16, v16, v17
	ds_bpermute_b32 v17, v187, v16
	global_store_dwordx4 v[60:61], v[56:59], off
	global_store_dwordx4 v[82:83], v[20:23], off nt
	global_store_dwordx4 v[82:83], v[24:27], off offset:16 nt
	v_cvt_pk_bf16_f32 v19, v22, v23
	v_cvt_pk_bf16_f32 v18, v20, v21
	s_nop 0
	v_lshl_add_u64 v[22:23], v[28:29], 1, s[30:31]
	v_cvt_pk_bf16_f32 v20, v24, v25
	v_cvt_pk_bf16_f32 v21, v26, v27
	global_store_dwordx4 v[22:23], v[18:21], off
	s_and_saveexec_b64 s[0:1], vcc
	s_cbranch_execz .LBB0_809
	v_lshl_add_u64 v[18:19], v[80:81], 2, s[12:13]
	s_waitcnt lgkmcnt(0)
	v_add_f32_e32 v16, v16, v17
	global_atomic_add_f32 v[18:19], v16, off
.LBB0_809:
	s_or_b64 exec, exec, s[0:1]
	s_waitcnt vmcnt(12)
	v_mov_b64_e32 v[40:41], v[228:229]
	v_mov_b64_e32 v[42:43], v[230:231]
	v_mov_b64_e32 v[44:45], v[232:233]
	v_mov_b64_e32 v[46:47], v[234:235]
	v_mov_b64_e32 v[32:33], v[236:237]
	v_mov_b64_e32 v[34:35], v[238:239]
	v_mov_b64_e32 v[36:37], v[240:241]
	v_mov_b64_e32 v[38:39], v[242:243]
	v_pk_add_f32 v[14:15], v[14:15], v[46:47]
	v_pk_add_f32 v[12:13], v[12:13], v[44:45]
	v_pk_add_f32 v[10:11], v[10:11], v[42:43]
	v_pk_add_f32 v[8:9], v[8:9], v[40:41]
	global_store_dwordx4 v[68:69], v[12:15], off nt
	global_store_dwordx4 v[68:69], v[8:11], off offset:16 nt
	v_cvt_pk_bf16_f32 v16, v12, v13
	v_cvt_pk_bf16_f32 v18, v8, v9
	v_pk_add_f32 v[6:7], v[6:7], v[38:39]
	v_mul_f32_e32 v13, v13, v13
	v_fmac_f32_e32 v13, v12, v12
	v_mul_f32_e32 v12, v15, v15
	v_fmac_f32_e32 v12, v14, v14
	v_mul_f32_e32 v9, v9, v9
	v_add_f32_e32 v12, v13, v12
	v_fmac_f32_e32 v9, v8, v8
	v_add_f32_e32 v8, v12, v9
	v_mul_f32_e32 v9, v11, v11
	v_fmac_f32_e32 v9, v10, v10
	v_pk_add_f32 v[4:5], v[4:5], v[36:37]
	s_waitcnt lgkmcnt(0)
	v_cvt_pk_bf16_f32 v17, v14, v15
	v_add_f32_e32 v14, v9, v8
	v_pk_add_f32 v[8:9], v[0:1], v[32:33]
	v_mul_f32_e32 v0, v5, v5
	v_mul_f32_e32 v1, v7, v7
	v_fmac_f32_e32 v0, v4, v4
	v_fmac_f32_e32 v1, v6, v6
	v_add_f32_e32 v0, v0, v1
	v_mul_f32_e32 v1, v9, v9
	v_cvt_pk_bf16_f32 v19, v10, v11
	v_pk_add_f32 v[10:11], v[2:3], v[34:35]
	v_fmac_f32_e32 v1, v8, v8
	v_add_f32_e32 v0, v0, v1
	v_mul_f32_e32 v1, v11, v11
	v_fmac_f32_e32 v1, v10, v10
	v_add_f32_e32 v0, v1, v0
	v_add_f32_e32 v0, v14, v0
	ds_bpermute_b32 v1, v186, v0
	v_lshlrev_b64 v[20:21], 10, v[64:65]
	v_lshl_add_u64 v[22:23], v[20:21], 0, v[162:163]
	v_lshl_add_u64 v[22:23], v[22:23], 1, s[30:31]
	v_lshl_add_u64 v[12:13], v[20:21], 0, v[160:161]
	s_waitcnt lgkmcnt(0)
	v_add_f32_e32 v0, v0, v1
	ds_bpermute_b32 v1, v187, v0
	global_store_dwordx4 v[22:23], v[16:19], off
	global_store_dwordx4 v[66:67], v[4:7], off nt
	global_store_dwordx4 v[66:67], v[8:11], off offset:16 nt
	v_cvt_pk_bf16_f32 v3, v6, v7
	v_cvt_pk_bf16_f32 v2, v4, v5
	s_nop 0
	v_lshl_add_u64 v[6:7], v[12:13], 1, s[30:31]
	v_cvt_pk_bf16_f32 v4, v8, v9
	v_cvt_pk_bf16_f32 v5, v10, v11
	global_store_dwordx4 v[6:7], v[2:5], off
	s_and_saveexec_b64 s[0:1], vcc
	s_cbranch_execz .LBB0_811
	v_lshl_add_u64 v[2:3], v[64:65], 2, s[12:13]
	s_waitcnt lgkmcnt(0)
	v_add_f32_e32 v0, v0, v1
	global_atomic_add_f32 v[2:3], v0, off

; #define EPI_IT_ROW(it) EPI_ROW((it) >> 2, (it) & 3)
; #define EPI_PACK8(v0, v1) (u32x4){pk2((v0)[0], (v0)[1]), pk2((v0)[2], (v0)[3]), pk2((v1)[0], (v1)[1]), pk2((v1)[2], (v1)[3])}
;     __device__ __forceinline__ void operator()(AccRef acc, const Unit& u, int wr, int wc, int fr, int fq) const {
;     ...
;         f32x4 xc[2][2], xn[2][2];
; #pragma unroll
;         for (int bj = 0; bj < 2; ++bj) { const size_t p = (size_t)EPI_IT_ROW(0) * DM + EPI_COL(bj); xc[bj][0] = *(const f32x4*)(xin + p); xc[bj][1] = *(const f32x4*)(xin + p + 4); }
; #pragma unroll
;         for (int it = 0; it < 8; ++it) { const int ai = it >> 2, m = it & 3, row = EPI_IT_ROW(it);
;             if (it + 1 < 8) {
; #pragma unroll
;                 for (int bj = 0; bj < 2; ++bj) { const size_t p = (size_t)EPI_IT_ROW(it + 1) * DM + EPI_COL(bj); xn[bj][0] = *(const f32x4*)(xin + p); xn[bj][1] = *(const f32x4*)(xin + p + 4); } }
;             float q = 0.f;
; #pragma unroll
;             for (int bj = 0; bj < 2; ++bj) { const size_t p = (size_t)row * DM + EPI_COL(bj);
;                 const f32x4 x0 = xc[bj][0] + acc[ai][bj][m][0], x1 = xc[bj][1] + acc[ai][bj][m][1];
;                 __builtin_nontemporal_store(x0, (f32x4*)(xout + p)); __builtin_nontemporal_store(x1, (f32x4*)(xout + p + 4));
;                 *(u32x4*)(xb + p) = EPI_PACK8(x0, x1);
;                 q += EPI_SQ8(x0, x1); }
;             q += __shfl_xor(q, 16); q += __shfl_xor(q, 32);
;             if (fq == 0) atomicAdd(ssout + row, q);
.LBB0_1317:
	s_lshl_b32 s1, s34, 8
	v_mov_b32_e32 v128, v180
	v_mov_b32_e32 v186, v177
	s_add_i32 s1, s1, s59
	s_lshl_b32 s0, s0, 8
	s_or_b32 s0, s0, s60
	v_add_u32_e32 v164, s1, v128
	v_ashrrev_i32_e32 v165, 31, v164
	v_lshl_add_u32 v162, v186, 3, s0
	v_lshlrev_b64 v[128:129], 12, v[164:165]
	v_ashrrev_i32_e32 v163, 31, v162
	v_add_u32_e32 v160, 0x80, v162
	v_lshl_add_u64 v[128:129], s[48:49], 0, v[128:129]
	v_lshlrev_b64 v[130:131], 2, v[162:163]
	v_ashrrev_i32_e32 v161, 31, v160
	v_lshl_add_u64 v[178:179], v[128:129], 0, v[130:131]
	v_lshlrev_b64 v[132:133], 2, v[160:161]
	global_load_dwordx4 v[170:173], v[178:179], off offset:16
	global_load_dwordx4 v[188:191], v[178:179], off
	v_lshl_add_u64 v[200:201], v[128:129], 0, v[132:133]
	global_load_dwordx4 v[192:195], v[200:201], off
	global_load_dwordx4 v[196:199], v[200:201], off offset:16
	v_add_u32_e32 v166, 16, v164
	v_ashrrev_i32_e32 v167, 31, v166
	v_lshlrev_b64 v[128:129], 12, v[166:167]
	v_lshl_add_u64 v[128:129], s[48:49], 0, v[128:129]
	v_lshl_add_u64 v[174:175], v[128:129], 0, v[130:131]
	v_lshl_add_u64 v[168:169], v[128:129], 0, v[132:133]
	global_load_dwordx4 v[136:139], v[174:175], off offset:16
	global_load_dwordx4 v[140:143], v[174:175], off
	global_load_dwordx4 v[128:131], v[168:169], off offset:16
	global_load_dwordx4 v[132:135], v[168:169], off
	v_add_u32_e32 v244, 32, v164
	v_ashrrev_i32_e32 v245, 31, v244
	v_lshlrev_b64 v[246:247], 12, v[244:245]
	v_lshl_add_u64 v[246:247], s[48:49], 0, v[246:247]
	v_lshl_add_u64 v[248:249], v[162:163], 2, v[246:247]
	v_lshl_add_u64 v[250:251], v[160:161], 2, v[246:247]
	global_load_dwordx4 v[206:209], v[248:249], off offset:16
	global_load_dwordx4 v[210:213], v[248:249], off
	global_load_dwordx4 v[214:217], v[250:251], off offset:16
	global_load_dwordx4 v[218:221], v[250:251], off
	v_add_u32_e32 v244, 48, v164
	v_ashrrev_i32_e32 v245, 31, v244
	v_lshlrev_b64 v[246:247], 12, v[244:245]
	v_lshl_add_u64 v[246:247], s[48:49], 0, v[246:247]
	v_lshl_add_u64 v[248:249], v[162:163], 2, v[246:247]
	v_lshl_add_u64 v[250:251], v[160:161], 2, v[246:247]
	global_load_dwordx4 v[228:231], v[248:249], off offset:16
	global_load_dwordx4 v[232:235], v[248:249], off
	global_load_dwordx4 v[236:239], v[250:251], off offset:16
	global_load_dwordx4 v[240:243], v[250:251], off
	v_and_b32_e32 v202, 64, v185
	v_xor_b32_e32 v187, 16, v185
	v_add_u32_e32 v202, 64, v202
	v_cmp_lt_i32_e64 s[0:1], v187, v202
	v_cmp_eq_u32_e32 vcc, 0, v186
	v_xor_b32_e32 v203, 32, v185
	v_cndmask_b32_e64 v186, v185, v187, s[0:1]
	v_lshlrev_b32_e32 v186, 2, v186
	v_cmp_lt_i32_e64 s[0:1], v203, v202
	s_waitcnt vmcnt(8)
	v_pk_add_f32 v[122:123], v[122:123], v[172:173]
	v_pk_add_f32 v[126:127], v[126:127], v[190:191]
	v_pk_add_f32 v[124:125], v[124:125], v[188:189]
	v_pk_add_f32 v[118:119], v[118:119], v[194:195]
	v_pk_add_f32 v[116:117], v[116:117], v[192:193]
	v_pk_add_f32 v[120:121], v[120:121], v[170:171]
	v_pk_add_f32 v[170:171], v[112:113], v[196:197]
	global_store_dwordx4 v[178:179], v[124:127], off nt
	global_store_dwordx4 v[178:179], v[120:123], off offset:16 nt
	v_cvt_pk_bf16_f32 v112, v124, v125
	v_cvt_pk_bf16_f32 v113, v126, v127
	v_mul_f32_e32 v178, v117, v117
	v_mul_f32_e32 v125, v125, v125
	v_mul_f32_e32 v127, v127, v127
	v_mul_f32_e32 v179, v119, v119
	v_pk_add_f32 v[172:173], v[114:115], v[198:199]
	v_cvt_pk_bf16_f32 v114, v120, v121
	v_cvt_pk_bf16_f32 v115, v122, v123
	v_mul_f32_e32 v121, v121, v121
	v_mul_f32_e32 v123, v123, v123
	v_mul_f32_e32 v189, v171, v171
	v_fmac_f32_e32 v125, v124, v124
	v_fmac_f32_e32 v127, v126, v126
	v_fmac_f32_e32 v178, v116, v116
	v_fmac_f32_e32 v179, v118, v118
	v_mul_f32_e32 v190, v173, v173
	v_fmac_f32_e32 v121, v120, v120
	v_fmac_f32_e32 v123, v122, v122
	v_fmac_f32_e32 v189, v170, v170
	v_add_f32_e32 v120, v125, v127
	v_add_f32_e32 v122, v178, v179
	v_fmac_f32_e32 v190, v172, v172
	v_add_f32_e32 v120, v120, v121
	v_add_f32_e32 v121, v122, v189
	v_add_f32_e32 v120, v123, v120
	v_add_f32_e32 v121, v190, v121
	v_add_f32_e32 v120, v120, v121
	ds_bpermute_b32 v121, v186, v120
	v_cndmask_b32_e64 v187, v185, v203, s[0:1]
	v_lshlrev_b64 v[202:203], 10, v[164:165]
	v_lshl_add_u64 v[204:205], v[202:203], 0, v[162:163]
	v_lshl_add_u64 v[204:205], v[204:205], 1, s[24:25]
	global_store_dwordx4 v[204:205], v[112:115], off
	global_store_dwordx4 v[200:201], v[116:119], off nt
	global_store_dwordx4 v[200:201], v[170:173], off offset:16 nt
	s_waitcnt lgkmcnt(0)
	v_add_f32_e32 v112, v120, v121
	v_lshlrev_b32_e32 v187, 2, v187
	ds_bpermute_b32 v113, v187, v112
	v_lshl_add_u64 v[202:203], v[202:203], 0, v[160:161]
	v_lshl_add_u64 v[114:115], v[202:203], 1, s[24:25]
	v_cvt_pk_bf16_f32 v188, v116, v117
	v_cvt_pk_bf16_f32 v189, v118, v119
	v_cvt_pk_bf16_f32 v190, v170, v171
	v_cvt_pk_bf16_f32 v191, v172, v173
	global_store_dwordx4 v[114:115], v[188:191], off
	s_and_saveexec_b64 s[0:1], vcc
	v_readlane_b32 s72, v254, 6
	v_readlane_b32 s73, v254, 7
	v_readlane_b32 s74, v254, 8
	v_readlane_b32 s75, v254, 9
	s_cbranch_execz .LBB0_1319
	v_lshl_add_u64 v[114:115], v[164:165], 2, s[10:11]
	s_waitcnt lgkmcnt(0)
	v_add_f32_e32 v112, v112, v113
	global_atomic_add_f32 v[114:115], v112, off
; #define EPI_IT_ROW(it) EPI_ROW((it) >> 2, (it) & 3)
; #define EPI_PACK8(v0, v1) (u32x4){pk2((v0)[0], (v0)[1]), pk2((v0)[2], (v0)[3]), pk2((v1)[0], (v1)[1]), pk2((v1)[2], (v1)[3])}
;     __device__ __forceinline__ void operator()(AccRef acc, const Unit& u, int wr, int wc, int fr, int fq) const {
;     ...
;         for (int it = 0; it < 8; ++it) { const int ai = it >> 2, m = it & 3, row = EPI_IT_ROW(it);
;             if (it + 1 < 8) {
; #pragma unroll
;                 for (int bj = 0; bj < 2; ++bj) { const size_t p = (size_t)EPI_IT_ROW(it + 1) * DM + EPI_COL(bj); xn[bj][0] = *(const f32x4*)(xin + p); xn[bj][1] = *(const f32x4*)(xin + p + 4); } }
;             float q = 0.f;
; #pragma unroll
;             for (int bj = 0; bj < 2; ++bj) { const size_t p = (size_t)row * DM + EPI_COL(bj);
;                 const f32x4 x0 = xc[bj][0] + acc[ai][bj][m][0], x1 = xc[bj][1] + acc[ai][bj][m][1];
;                 __builtin_nontemporal_store(x0, (f32x4*)(xout + p)); __builtin_nontemporal_store(x1, (f32x4*)(xout + p + 4));
;                 *(u32x4*)(xb + p) = EPI_PACK8(x0, x1);
;                 q += EPI_SQ8(x0, x1); }
;             q += __shfl_xor(q, 16); q += __shfl_xor(q, 32);
;             if (fq == 0) atomicAdd(ssout + row, q);
; #pragma unroll
;             for (int bj = 0; bj < 2; ++bj) { xc[bj][0] = xn[bj][0]; xc[bj][1] = xn[bj][1]; } }
.LBB0_1319:
	s_or_b64 exec, exec, s[0:1]
	v_add_u32_e32 v170, 32, v164
	v_ashrrev_i32_e32 v171, 31, v170
	s_waitcnt lgkmcnt(0)
	v_lshlrev_b64 v[112:113], 12, v[170:171]
	v_lshl_add_u64 v[112:113], s[48:49], 0, v[112:113]
	v_lshl_add_u64 v[178:179], v[162:163], 2, v[112:113]
	v_lshl_add_u64 v[172:173], v[160:161], 2, v[112:113]
	v_pk_add_f32 v[110:111], v[110:111], v[142:143]
	v_pk_add_f32 v[108:109], v[108:109], v[140:141]
	v_pk_add_f32 v[106:107], v[106:107], v[138:139]
	v_pk_add_f32 v[104:105], v[104:105], v[136:137]
	global_store_dwordx4 v[174:175], v[108:111], off nt
	global_store_dwordx4 v[174:175], v[104:107], off offset:16 nt
	v_cvt_pk_bf16_f32 v136, v108, v109
	v_cvt_pk_bf16_f32 v138, v104, v105
	v_pk_add_f32 v[102:103], v[102:103], v[134:135]
	v_mul_f32_e32 v109, v109, v109
	v_fmac_f32_e32 v109, v108, v108
	v_mul_f32_e32 v108, v111, v111
	v_fmac_f32_e32 v108, v110, v110
	v_mul_f32_e32 v105, v105, v105
	v_add_f32_e32 v108, v109, v108
	v_fmac_f32_e32 v105, v104, v104
	v_add_f32_e32 v104, v108, v105
	v_mul_f32_e32 v105, v107, v107
	v_fmac_f32_e32 v105, v106, v106
	v_pk_add_f32 v[100:101], v[100:101], v[132:133]
	v_cvt_pk_bf16_f32 v137, v110, v111
	v_add_f32_e32 v110, v105, v104
	v_pk_add_f32 v[104:105], v[96:97], v[128:129]
	v_mul_f32_e32 v96, v101, v101
	v_mul_f32_e32 v97, v103, v103
	v_fmac_f32_e32 v96, v100, v100
	v_fmac_f32_e32 v97, v102, v102
	v_add_f32_e32 v96, v96, v97
	v_mul_f32_e32 v97, v105, v105
	v_cvt_pk_bf16_f32 v139, v106, v107
	v_pk_add_f32 v[106:107], v[98:99], v[130:131]
	v_fmac_f32_e32 v97, v104, v104
	v_add_f32_e32 v96, v96, v97
	v_mul_f32_e32 v97, v107, v107
	v_fmac_f32_e32 v97, v106, v106
	v_add_f32_e32 v96, v97, v96
	v_add_f32_e32 v96, v110, v96
	ds_bpermute_b32 v97, v186, v96
	v_lshlrev_b64 v[188:189], 10, v[166:167]
	v_lshl_add_u64 v[190:191], v[188:189], 0, v[162:163]
	v_lshl_add_u64 v[140:141], v[190:191], 1, s[24:25]
	v_lshl_add_u64 v[108:109], v[188:189], 0, v[160:161]
	s_waitcnt lgkmcnt(0)
	v_add_f32_e32 v96, v96, v97
	ds_bpermute_b32 v97, v187, v96
	global_store_dwordx4 v[140:141], v[136:139], off
	global_store_dwordx4 v[168:169], v[100:103], off nt
	global_store_dwordx4 v[168:169], v[104:107], off offset:16 nt
	v_cvt_pk_bf16_f32 v99, v102, v103
	v_cvt_pk_bf16_f32 v98, v100, v101
	s_nop 0
	v_lshl_add_u64 v[102:103], v[108:109], 1, s[24:25]
	v_cvt_pk_bf16_f32 v100, v104, v105
	v_cvt_pk_bf16_f32 v101, v106, v107
	global_store_dwordx4 v[102:103], v[98:101], off
	s_and_saveexec_b64 s[0:1], vcc
	s_cbranch_execz .LBB0_1321
	v_lshl_add_u64 v[98:99], v[166:167], 2, s[10:11]
	s_waitcnt lgkmcnt(0)
	v_add_f32_e32 v96, v96, v97
	global_atomic_add_f32 v[98:99], v96, off
.LBB0_1321:
	s_or_b64 exec, exec, s[0:1]
	s_waitcnt vmcnt(16)
	v_mov_b64_e32 v[120:121], v[206:207]
	v_mov_b64_e32 v[122:123], v[208:209]
	v_mov_b64_e32 v[124:125], v[210:211]
	v_mov_b64_e32 v[126:127], v[212:213]
	v_mov_b64_e32 v[112:113], v[214:215]
	v_mov_b64_e32 v[114:115], v[216:217]
	v_mov_b64_e32 v[116:117], v[218:219]
	v_mov_b64_e32 v[118:119], v[220:221]
	v_add_u32_e32 v244, 128, v164
	v_ashrrev_i32_e32 v245, 31, v244
	v_lshlrev_b64 v[246:247], 12, v[244:245]
	v_lshl_add_u64 v[246:247], s[48:49], 0, v[246:247]
	v_lshl_add_u64 v[248:249], v[162:163], 2, v[246:247]
	v_lshl_add_u64 v[250:251], v[160:161], 2, v[246:247]
	global_load_dwordx4 v[206:209], v[248:249], off offset:16
	global_load_dwordx4 v[210:213], v[248:249], off
	global_load_dwordx4 v[214:217], v[250:251], off offset:16
	global_load_dwordx4 v[218:221], v[250:251], off
	v_add_u32_e32 v128, 48, v164
	v_ashrrev_i32_e32 v129, 31, v128
	s_waitcnt lgkmcnt(0)
	v_lshlrev_b64 v[96:97], 12, v[128:129]
	v_lshl_add_u64 v[96:97], s[48:49], 0, v[96:97]
	v_lshl_add_u64 v[132:133], v[162:163], 2, v[96:97]
	v_lshl_add_u64 v[130:131], v[160:161], 2, v[96:97]
	v_pk_add_f32 v[94:95], v[94:95], v[126:127]
	v_pk_add_f32 v[92:93], v[92:93], v[124:125]
	v_pk_add_f32 v[90:91], v[90:91], v[122:123]
	v_pk_add_f32 v[88:89], v[88:89], v[120:121]
	global_store_dwordx4 v[178:179], v[92:95], off nt
	global_store_dwordx4 v[178:179], v[88:91], off offset:16 nt
	v_cvt_pk_bf16_f32 v120, v92, v93
	v_cvt_pk_bf16_f32 v122, v88, v89
	v_pk_add_f32 v[86:87], v[86:87], v[118:119]
	v_mul_f32_e32 v93, v93, v93
	v_fmac_f32_e32 v93, v92, v92
	v_mul_f32_e32 v92, v95, v95
	v_fmac_f32_e32 v92, v94, v94
	v_mul_f32_e32 v89, v89, v89
	v_add_f32_e32 v92, v93, v92
	v_fmac_f32_e32 v89, v88, v88
	v_add_f32_e32 v88, v92, v89
	v_mul_f32_e32 v89, v91, v91
	v_fmac_f32_e32 v89, v90, v90
	v_pk_add_f32 v[84:85], v[84:85], v[116:117]
	v_cvt_pk_bf16_f32 v121, v94, v95
	v_add_f32_e32 v94, v89, v88
	v_pk_add_f32 v[88:89], v[80:81], v[112:113]
	v_mul_f32_e32 v80, v85, v85
	v_mul_f32_e32 v81, v87, v87
	v_fmac_f32_e32 v80, v84, v84
	v_fmac_f32_e32 v81, v86, v86
	v_add_f32_e32 v80, v80, v81
	v_mul_f32_e32 v81, v89, v89
	v_cvt_pk_bf16_f32 v123, v90, v91
	v_pk_add_f32 v[90:91], v[82:83], v[114:115]
	v_fmac_f32_e32 v81, v88, v88
	v_add_f32_e32 v80, v80, v81
	v_mul_f32_e32 v81, v91, v91
	v_fmac_f32_e32 v81, v90, v90
	v_add_f32_e32 v80, v81, v80
	v_add_f32_e32 v80, v94, v80
	ds_bpermute_b32 v81, v186, v80
	v_lshlrev_b64 v[134:135], 10, v[170:171]
	v_lshl_add_u64 v[136:137], v[134:135], 0, v[162:163]
	v_lshl_add_u64 v[124:125], v[136:137], 1, s[24:25]
	v_lshl_add_u64 v[92:93], v[134:135], 0, v[160:161]
	s_waitcnt lgkmcnt(0)
	v_add_f32_e32 v80, v80, v81
	ds_bpermute_b32 v81, v187, v80
	global_store_dwordx4 v[124:125], v[120:123], off
	global_store_dwordx4 v[172:173], v[84:87], off nt
	global_store_dwordx4 v[172:173], v[88:91], off offset:16 nt
	v_cvt_pk_bf16_f32 v83, v86, v87
	v_cvt_pk_bf16_f32 v82, v84, v85
	s_nop 0
	v_lshl_add_u64 v[86:87], v[92:93], 1, s[24:25]
	v_cvt_pk_bf16_f32 v84, v88, v89
	v_cvt_pk_bf16_f32 v85, v90, v91
	global_store_dwordx4 v[86:87], v[82:85], off
	s_and_saveexec_b64 s[0:1], vcc
	s_cbranch_execz .LBB0_1323
	v_lshl_add_u64 v[82:83], v[170:171], 2, s[10:11]
	s_waitcnt lgkmcnt(0)
	v_add_f32_e32 v80, v80, v81
	global_atomic_add_f32 v[82:83], v80, off
; #define EPI_IT_ROW(it) EPI_ROW((it) >> 2, (it) & 3)
; #define EPI_PACK8(v0, v1) (u32x4){pk2((v0)[0], (v0)[1]), pk2((v0)[2], (v0)[3]), pk2((v1)[0], (v1)[1]), pk2((v1)[2], (v1)[3])}
;     __device__ __forceinline__ void operator()(AccRef acc, const Unit& u, int wr, int wc, int fr, int fq) const {
;     ...
;         for (int it = 0; it < 8; ++it) { const int ai = it >> 2, m = it & 3, row = EPI_IT_ROW(it);
;             if (it + 1 < 8) {
; #pragma unroll
;                 for (int bj = 0; bj < 2; ++bj) { const size_t p = (size_t)EPI_IT_ROW(it + 1) * DM + EPI_COL(bj); xn[bj][0] = *(const f32x4*)(xin + p); xn[bj][1] = *(const f32x4*)(xin + p + 4); } }
;             float q = 0.f;
; #pragma unroll
;             for (int bj = 0; bj < 2; ++bj) { const size_t p = (size_t)row * DM + EPI_COL(bj);
;                 const f32x4 x0 = xc[bj][0] + acc[ai][bj][m][0], x1 = xc[bj][1] + acc[ai][bj][m][1];
;                 __builtin_nontemporal_store(x0, (f32x4*)(xout + p)); __builtin_nontemporal_store(x1, (f32x4*)(xout + p + 4));
;                 *(u32x4*)(xb + p) = EPI_PACK8(x0, x1);
;                 q += EPI_SQ8(x0, x1); }
;             q += __shfl_xor(q, 16); q += __shfl_xor(q, 32);
;             if (fq == 0) atomicAdd(ssout + row, q);
; #pragma unroll
;             for (int bj = 0; bj < 2; ++bj) { xc[bj][0] = xn[bj][0]; xc[bj][1] = xn[bj][1]; } }
.LBB0_1323:
	s_or_b64 exec, exec, s[0:1]
	s_waitcnt vmcnt(22)
	v_mov_b64_e32 v[104:105], v[228:229]
	v_mov_b64_e32 v[106:107], v[230:231]
	v_mov_b64_e32 v[108:109], v[232:233]
	v_mov_b64_e32 v[110:111], v[234:235]
	v_mov_b64_e32 v[96:97], v[236:237]
	v_mov_b64_e32 v[98:99], v[238:239]
	v_mov_b64_e32 v[100:101], v[240:241]
	v_mov_b64_e32 v[102:103], v[242:243]
	v_add_u32_e32 v244, 144, v164
	v_ashrrev_i32_e32 v245, 31, v244
	v_lshlrev_b64 v[246:247], 12, v[244:245]
	v_lshl_add_u64 v[246:247], s[48:49], 0, v[246:247]
	v_lshl_add_u64 v[248:249], v[162:163], 2, v[246:247]
	v_lshl_add_u64 v[250:251], v[160:161], 2, v[246:247]
	global_load_dwordx4 v[228:231], v[248:249], off offset:16
	global_load_dwordx4 v[232:235], v[248:249], off
	global_load_dwordx4 v[236:239], v[250:251], off offset:16
	global_load_dwordx4 v[240:243], v[250:251], off
	v_add_u32_e32 v112, 0x80, v164
	v_ashrrev_i32_e32 v113, 31, v112
	s_waitcnt lgkmcnt(0)
	v_lshlrev_b64 v[80:81], 12, v[112:113]
	v_lshl_add_u64 v[80:81], s[48:49], 0, v[80:81]
	v_lshl_add_u64 v[116:117], v[162:163], 2, v[80:81]
	v_lshl_add_u64 v[114:115], v[160:161], 2, v[80:81]
	v_pk_add_f32 v[78:79], v[78:79], v[110:111]
	v_pk_add_f32 v[76:77], v[76:77], v[108:109]
	v_pk_add_f32 v[74:75], v[74:75], v[106:107]
	v_pk_add_f32 v[72:73], v[72:73], v[104:105]
	global_store_dwordx4 v[132:133], v[76:79], off nt
	global_store_dwordx4 v[132:133], v[72:75], off offset:16 nt
	v_cvt_pk_bf16_f32 v104, v76, v77
	v_cvt_pk_bf16_f32 v106, v72, v73
	v_pk_add_f32 v[70:71], v[70:71], v[102:103]
	v_mul_f32_e32 v77, v77, v77
	v_fmac_f32_e32 v77, v76, v76
	v_mul_f32_e32 v76, v79, v79
	v_fmac_f32_e32 v76, v78, v78
	v_mul_f32_e32 v73, v73, v73
	v_add_f32_e32 v76, v77, v76
	v_fmac_f32_e32 v73, v72, v72
	v_add_f32_e32 v72, v76, v73
	v_mul_f32_e32 v73, v75, v75
	v_fmac_f32_e32 v73, v74, v74
	v_pk_add_f32 v[68:69], v[68:69], v[100:101]
	v_cvt_pk_bf16_f32 v105, v78, v79
	v_add_f32_e32 v78, v73, v72
	v_pk_add_f32 v[72:73], v[64:65], v[96:97]
	v_mul_f32_e32 v64, v69, v69
	v_mul_f32_e32 v65, v71, v71
	v_fmac_f32_e32 v64, v68, v68
	v_fmac_f32_e32 v65, v70, v70
	v_add_f32_e32 v64, v64, v65
	v_mul_f32_e32 v65, v73, v73
	v_cvt_pk_bf16_f32 v107, v74, v75
	v_pk_add_f32 v[74:75], v[66:67], v[98:99]
	v_fmac_f32_e32 v65, v72, v72
	v_add_f32_e32 v64, v64, v65
	v_mul_f32_e32 v65, v75, v75
	v_fmac_f32_e32 v65, v74, v74
	v_add_f32_e32 v64, v65, v64
	v_add_f32_e32 v64, v78, v64
	ds_bpermute_b32 v65, v186, v64
	v_lshlrev_b64 v[118:119], 10, v[128:129]
	v_lshl_add_u64 v[120:121], v[118:119], 0, v[162:163]
	v_lshl_add_u64 v[108:109], v[120:121], 1, s[24:25]
	v_lshl_add_u64 v[76:77], v[118:119], 0, v[160:161]
	s_waitcnt lgkmcnt(0)
	v_add_f32_e32 v64, v64, v65
	ds_bpermute_b32 v65, v187, v64
	global_store_dwordx4 v[108:109], v[104:107], off
	global_store_dwordx4 v[130:131], v[68:71], off nt
	global_store_dwordx4 v[130:131], v[72:75], off offset:16 nt
	v_cvt_pk_bf16_f32 v67, v70, v71
	v_cvt_pk_bf16_f32 v66, v68, v69
	s_nop 0
	v_lshl_add_u64 v[70:71], v[76:77], 1, s[24:25]
	v_cvt_pk_bf16_f32 v68, v72, v73
	v_cvt_pk_bf16_f32 v69, v74, v75
	global_store_dwordx4 v[70:71], v[66:69], off
	s_and_saveexec_b64 s[0:1], vcc
	s_cbranch_execz .LBB0_1325
	v_lshl_add_u64 v[66:67], v[128:129], 2, s[10:11]
	s_waitcnt lgkmcnt(0)
	v_add_f32_e32 v64, v64, v65
	global_atomic_add_f32 v[66:67], v64, off
.LBB0_1325:
	s_or_b64 exec, exec, s[0:1]
	s_waitcnt vmcnt(16)
	v_mov_b64_e32 v[88:89], v[206:207]
	v_mov_b64_e32 v[90:91], v[208:209]
	v_mov_b64_e32 v[92:93], v[210:211]
	v_mov_b64_e32 v[94:95], v[212:213]
	v_mov_b64_e32 v[80:81], v[214:215]
	v_mov_b64_e32 v[82:83], v[216:217]
	v_mov_b64_e32 v[84:85], v[218:219]
	v_mov_b64_e32 v[86:87], v[220:221]
	v_add_u32_e32 v244, 160, v164
	v_ashrrev_i32_e32 v245, 31, v244
	v_lshlrev_b64 v[246:247], 12, v[244:245]
	v_lshl_add_u64 v[246:247], s[48:49], 0, v[246:247]
	v_lshl_add_u64 v[248:249], v[162:163], 2, v[246:247]
	v_lshl_add_u64 v[250:251], v[160:161], 2, v[246:247]
	global_load_dwordx4 v[206:209], v[248:249], off offset:16
	global_load_dwordx4 v[210:213], v[248:249], off
	global_load_dwordx4 v[214:217], v[250:251], off offset:16
	global_load_dwordx4 v[218:221], v[250:251], off
	v_add_u32_e32 v96, 0x90, v164
	v_ashrrev_i32_e32 v97, 31, v96
	s_waitcnt lgkmcnt(0)
	v_lshlrev_b64 v[64:65], 12, v[96:97]
	v_lshl_add_u64 v[64:65], s[48:49], 0, v[64:65]
	v_lshl_add_u64 v[100:101], v[162:163], 2, v[64:65]
	v_lshl_add_u64 v[98:99], v[160:161], 2, v[64:65]
	v_pk_add_f32 v[62:63], v[62:63], v[94:95]
	v_pk_add_f32 v[60:61], v[60:61], v[92:93]
	v_pk_add_f32 v[58:59], v[58:59], v[90:91]
	v_pk_add_f32 v[56:57], v[56:57], v[88:89]
	global_store_dwordx4 v[116:117], v[60:63], off nt
	global_store_dwordx4 v[116:117], v[56:59], off offset:16 nt
	v_cvt_pk_bf16_f32 v88, v60, v61
	v_cvt_pk_bf16_f32 v90, v56, v57
	v_pk_add_f32 v[54:55], v[54:55], v[86:87]
	v_mul_f32_e32 v61, v61, v61
	v_fmac_f32_e32 v61, v60, v60
	v_mul_f32_e32 v60, v63, v63
	v_fmac_f32_e32 v60, v62, v62
	v_mul_f32_e32 v57, v57, v57
	v_add_f32_e32 v60, v61, v60
	v_fmac_f32_e32 v57, v56, v56
	v_add_f32_e32 v56, v60, v57
	v_mul_f32_e32 v57, v59, v59
	v_fmac_f32_e32 v57, v58, v58
	v_pk_add_f32 v[52:53], v[52:53], v[84:85]
	v_cvt_pk_bf16_f32 v89, v62, v63
	v_add_f32_e32 v62, v57, v56
	v_pk_add_f32 v[56:57], v[48:49], v[80:81]
	v_mul_f32_e32 v48, v53, v53
	v_mul_f32_e32 v49, v55, v55
	v_fmac_f32_e32 v48, v52, v52
	v_fmac_f32_e32 v49, v54, v54
	v_add_f32_e32 v48, v48, v49
	v_mul_f32_e32 v49, v57, v57
	v_cvt_pk_bf16_f32 v91, v58, v59
	v_pk_add_f32 v[58:59], v[50:51], v[82:83]
	v_fmac_f32_e32 v49, v56, v56
	v_add_f32_e32 v48, v48, v49
	v_mul_f32_e32 v49, v59, v59
	v_fmac_f32_e32 v49, v58, v58
	v_add_f32_e32 v48, v49, v48
	v_add_f32_e32 v48, v62, v48
	ds_bpermute_b32 v49, v186, v48
	v_lshlrev_b64 v[102:103], 10, v[112:113]
	v_lshl_add_u64 v[104:105], v[102:103], 0, v[162:163]
	v_lshl_add_u64 v[92:93], v[104:105], 1, s[24:25]
	v_lshl_add_u64 v[60:61], v[102:103], 0, v[160:161]
	s_waitcnt lgkmcnt(0)
	v_add_f32_e32 v48, v48, v49
	ds_bpermute_b32 v49, v187, v48
	global_store_dwordx4 v[92:93], v[88:91], off
	global_store_dwordx4 v[114:115], v[52:55], off nt
	global_store_dwordx4 v[114:115], v[56:59], off offset:16 nt
	v_cvt_pk_bf16_f32 v51, v54, v55
	v_cvt_pk_bf16_f32 v50, v52, v53
	s_nop 0
	v_lshl_add_u64 v[54:55], v[60:61], 1, s[24:25]
	v_cvt_pk_bf16_f32 v52, v56, v57
	v_cvt_pk_bf16_f32 v53, v58, v59
	global_store_dwordx4 v[54:55], v[50:53], off
	s_and_saveexec_b64 s[0:1], vcc
	s_cbranch_execz .LBB0_1327
	v_lshl_add_u64 v[50:51], v[112:113], 2, s[10:11]
	s_waitcnt lgkmcnt(0)
	v_add_f32_e32 v48, v48, v49
	global_atomic_add_f32 v[50:51], v48, off
; #define EPI_IT_ROW(it) EPI_ROW((it) >> 2, (it) & 3)
; #define EPI_PACK8(v0, v1) (u32x4){pk2((v0)[0], (v0)[1]), pk2((v0)[2], (v0)[3]), pk2((v1)[0], (v1)[1]), pk2((v1)[2], (v1)[3])}
;     __device__ __forceinline__ void operator()(AccRef acc, const Unit& u, int wr, int wc, int fr, int fq) const {
;     ...
;         for (int it = 0; it < 8; ++it) { const int ai = it >> 2, m = it & 3, row = EPI_IT_ROW(it);
;             if (it + 1 < 8) {
; #pragma unroll
;                 for (int bj = 0; bj < 2; ++bj) { const size_t p = (size_t)EPI_IT_ROW(it + 1) * DM + EPI_COL(bj); xn[bj][0] = *(const f32x4*)(xin + p); xn[bj][1] = *(const f32x4*)(xin + p + 4); } }
;             float q = 0.f;
; #pragma unroll
;             for (int bj = 0; bj < 2; ++bj) { const size_t p = (size_t)row * DM + EPI_COL(bj);
;                 const f32x4 x0 = xc[bj][0] + acc[ai][bj][m][0], x1 = xc[bj][1] + acc[ai][bj][m][1];
;                 __builtin_nontemporal_store(x0, (f32x4*)(xout + p)); __builtin_nontemporal_store(x1, (f32x4*)(xout + p + 4));
;                 *(u32x4*)(xb + p) = EPI_PACK8(x0, x1);
;                 q += EPI_SQ8(x0, x1); }
;             q += __shfl_xor(q, 16); q += __shfl_xor(q, 32);
;             if (fq == 0) atomicAdd(ssout + row, q);
; #pragma unroll
;             for (int bj = 0; bj < 2; ++bj) { xc[bj][0] = xn[bj][0]; xc[bj][1] = xn[bj][1]; } }
.LBB0_1327:
	s_or_b64 exec, exec, s[0:1]
	s_waitcnt vmcnt(16)
	v_mov_b64_e32 v[72:73], v[228:229]
	v_mov_b64_e32 v[74:75], v[230:231]
	v_mov_b64_e32 v[76:77], v[232:233]
	v_mov_b64_e32 v[78:79], v[234:235]
	v_mov_b64_e32 v[64:65], v[236:237]
	v_mov_b64_e32 v[66:67], v[238:239]
	v_mov_b64_e32 v[68:69], v[240:241]
	v_mov_b64_e32 v[70:71], v[242:243]
	v_add_u32_e32 v244, 176, v164
	v_ashrrev_i32_e32 v245, 31, v244
	v_lshlrev_b64 v[246:247], 12, v[244:245]
	v_lshl_add_u64 v[246:247], s[48:49], 0, v[246:247]
	v_lshl_add_u64 v[248:249], v[162:163], 2, v[246:247]
	v_lshl_add_u64 v[250:251], v[160:161], 2, v[246:247]
	global_load_dwordx4 v[228:231], v[248:249], off offset:16
	global_load_dwordx4 v[232:235], v[248:249], off
	global_load_dwordx4 v[236:239], v[250:251], off offset:16
	global_load_dwordx4 v[240:243], v[250:251], off
	v_add_u32_e32 v80, 0xa0, v164
	v_ashrrev_i32_e32 v81, 31, v80
	s_waitcnt lgkmcnt(0)
	v_lshlrev_b64 v[48:49], 12, v[80:81]
	v_lshl_add_u64 v[48:49], s[48:49], 0, v[48:49]
	v_lshl_add_u64 v[84:85], v[162:163], 2, v[48:49]
	v_lshl_add_u64 v[82:83], v[160:161], 2, v[48:49]
	v_pk_add_f32 v[46:47], v[46:47], v[78:79]
	v_pk_add_f32 v[44:45], v[44:45], v[76:77]
	v_pk_add_f32 v[42:43], v[42:43], v[74:75]
	v_pk_add_f32 v[40:41], v[40:41], v[72:73]
	global_store_dwordx4 v[100:101], v[44:47], off nt
	global_store_dwordx4 v[100:101], v[40:43], off offset:16 nt
	v_cvt_pk_bf16_f32 v72, v44, v45
	v_cvt_pk_bf16_f32 v74, v40, v41
	v_pk_add_f32 v[38:39], v[38:39], v[70:71]
	v_mul_f32_e32 v45, v45, v45
	v_fmac_f32_e32 v45, v44, v44
	v_mul_f32_e32 v44, v47, v47
	v_fmac_f32_e32 v44, v46, v46
	v_mul_f32_e32 v41, v41, v41
	v_add_f32_e32 v44, v45, v44
	v_fmac_f32_e32 v41, v40, v40
	v_add_f32_e32 v40, v44, v41
	v_mul_f32_e32 v41, v43, v43
	v_fmac_f32_e32 v41, v42, v42
	v_pk_add_f32 v[36:37], v[36:37], v[68:69]
	v_cvt_pk_bf16_f32 v73, v46, v47
	v_add_f32_e32 v46, v41, v40
	v_pk_add_f32 v[40:41], v[32:33], v[64:65]
	v_mul_f32_e32 v32, v37, v37
	v_mul_f32_e32 v33, v39, v39
	v_fmac_f32_e32 v32, v36, v36
	v_fmac_f32_e32 v33, v38, v38
	v_add_f32_e32 v32, v32, v33
	v_mul_f32_e32 v33, v41, v41
	v_cvt_pk_bf16_f32 v75, v42, v43
	v_pk_add_f32 v[42:43], v[34:35], v[66:67]
	v_fmac_f32_e32 v33, v40, v40
	v_add_f32_e32 v32, v32, v33
	v_mul_f32_e32 v33, v43, v43
	v_fmac_f32_e32 v33, v42, v42
	v_add_f32_e32 v32, v33, v32
	v_add_f32_e32 v32, v46, v32
	ds_bpermute_b32 v33, v186, v32
	v_lshlrev_b64 v[86:87], 10, v[96:97]
	v_lshl_add_u64 v[88:89], v[86:87], 0, v[162:163]
	v_lshl_add_u64 v[76:77], v[88:89], 1, s[24:25]
	v_lshl_add_u64 v[44:45], v[86:87], 0, v[160:161]
	s_waitcnt lgkmcnt(0)
	v_add_f32_e32 v32, v32, v33
	ds_bpermute_b32 v33, v187, v32
	global_store_dwordx4 v[76:77], v[72:75], off
	global_store_dwordx4 v[98:99], v[36:39], off nt
	global_store_dwordx4 v[98:99], v[40:43], off offset:16 nt
	v_cvt_pk_bf16_f32 v35, v38, v39
	v_cvt_pk_bf16_f32 v34, v36, v37
	s_nop 0
	v_lshl_add_u64 v[38:39], v[44:45], 1, s[24:25]
	v_cvt_pk_bf16_f32 v36, v40, v41
	v_cvt_pk_bf16_f32 v37, v42, v43
	global_store_dwordx4 v[38:39], v[34:37], off
	s_and_saveexec_b64 s[0:1], vcc
	s_cbranch_execz .LBB0_1329
	v_lshl_add_u64 v[34:35], v[96:97], 2, s[10:11]
	s_waitcnt lgkmcnt(0)
	v_add_f32_e32 v32, v32, v33
	global_atomic_add_f32 v[34:35], v32, off
; #define EPI_IT_ROW(it) EPI_ROW((it) >> 2, (it) & 3)
; #define EPI_PACK8(v0, v1) (u32x4){pk2((v0)[0], (v0)[1]), pk2((v0)[2], (v0)[3]), pk2((v1)[0], (v1)[1]), pk2((v1)[2], (v1)[3])}
;     __device__ __forceinline__ void operator()(AccRef acc, const Unit& u, int wr, int wc, int fr, int fq) const {
;     ...
;         for (int it = 0; it < 8; ++it) { const int ai = it >> 2, m = it & 3, row = EPI_IT_ROW(it);
;             if (it + 1 < 8) {
; #pragma unroll
;                 for (int bj = 0; bj < 2; ++bj) { const size_t p = (size_t)EPI_IT_ROW(it + 1) * DM + EPI_COL(bj); xn[bj][0] = *(const f32x4*)(xin + p); xn[bj][1] = *(const f32x4*)(xin + p + 4); } }
;             float q = 0.f;
; #pragma unroll
;             for (int bj = 0; bj < 2; ++bj) { const size_t p = (size_t)row * DM + EPI_COL(bj);
;                 const f32x4 x0 = xc[bj][0] + acc[ai][bj][m][0], x1 = xc[bj][1] + acc[ai][bj][m][1];
;                 __builtin_nontemporal_store(x0, (f32x4*)(xout + p)); __builtin_nontemporal_store(x1, (f32x4*)(xout + p + 4));
;                 *(u32x4*)(xb + p) = EPI_PACK8(x0, x1);
;                 q += EPI_SQ8(x0, x1); }
;             q += __shfl_xor(q, 16); q += __shfl_xor(q, 32);
;             if (fq == 0) atomicAdd(ssout + row, q);
; #pragma unroll
;             for (int bj = 0; bj < 2; ++bj) { xc[bj][0] = xn[bj][0]; xc[bj][1] = xn[bj][1]; } }
.LBB0_1329:
	s_or_b64 exec, exec, s[0:1]
	s_waitcnt vmcnt(16)
	v_mov_b64_e32 v[56:57], v[206:207]
	v_mov_b64_e32 v[58:59], v[208:209]
	v_mov_b64_e32 v[60:61], v[210:211]
	v_mov_b64_e32 v[62:63], v[212:213]
	v_mov_b64_e32 v[48:49], v[214:215]
	v_mov_b64_e32 v[50:51], v[216:217]
	v_mov_b64_e32 v[52:53], v[218:219]
	v_mov_b64_e32 v[54:55], v[220:221]
	v_add_u32_e32 v64, 0xb0, v164
	v_ashrrev_i32_e32 v65, 31, v64
	s_waitcnt lgkmcnt(0)
	v_lshlrev_b64 v[32:33], 12, v[64:65]
	v_lshl_add_u64 v[32:33], s[48:49], 0, v[32:33]
	v_lshl_add_u64 v[68:69], v[162:163], 2, v[32:33]
	v_lshl_add_u64 v[66:67], v[160:161], 2, v[32:33]
	v_pk_add_f32 v[30:31], v[30:31], v[62:63]
	v_pk_add_f32 v[28:29], v[28:29], v[60:61]
	v_pk_add_f32 v[26:27], v[26:27], v[58:59]
	v_pk_add_f32 v[24:25], v[24:25], v[56:57]
	global_store_dwordx4 v[84:85], v[28:31], off nt
	global_store_dwordx4 v[84:85], v[24:27], off offset:16 nt
	v_cvt_pk_bf16_f32 v56, v28, v29
	v_cvt_pk_bf16_f32 v58, v24, v25
	v_pk_add_f32 v[22:23], v[22:23], v[54:55]
	v_mul_f32_e32 v29, v29, v29
	v_fmac_f32_e32 v29, v28, v28
	v_mul_f32_e32 v28, v31, v31
	v_fmac_f32_e32 v28, v30, v30
	v_mul_f32_e32 v25, v25, v25
	v_add_f32_e32 v28, v29, v28
	v_fmac_f32_e32 v25, v24, v24
	v_add_f32_e32 v24, v28, v25
	v_mul_f32_e32 v25, v27, v27
	v_fmac_f32_e32 v25, v26, v26
	v_pk_add_f32 v[20:21], v[20:21], v[52:53]
	v_cvt_pk_bf16_f32 v57, v30, v31
	v_add_f32_e32 v30, v25, v24
	v_pk_add_f32 v[24:25], v[16:17], v[48:49]
	v_mul_f32_e32 v16, v21, v21
	v_mul_f32_e32 v17, v23, v23
	v_fmac_f32_e32 v16, v20, v20
	v_fmac_f32_e32 v17, v22, v22
	v_add_f32_e32 v16, v16, v17
	v_mul_f32_e32 v17, v25, v25
	v_cvt_pk_bf16_f32 v59, v26, v27
	v_pk_add_f32 v[26:27], v[18:19], v[50:51]
	v_fmac_f32_e32 v17, v24, v24
	v_add_f32_e32 v16, v16, v17
	v_mul_f32_e32 v17, v27, v27
	v_fmac_f32_e32 v17, v26, v26
	v_add_f32_e32 v16, v17, v16
	v_add_f32_e32 v16, v30, v16
	ds_bpermute_b32 v17, v186, v16
	v_lshlrev_b64 v[70:71], 10, v[80:81]
	v_lshl_add_u64 v[72:73], v[70:71], 0, v[162:163]
	v_lshl_add_u64 v[60:61], v[72:73], 1, s[24:25]
	v_lshl_add_u64 v[28:29], v[70:71], 0, v[160:161]
	s_waitcnt lgkmcnt(0)
	v_add_f32_e32 v16, v16, v17
	ds_bpermute_b32 v17, v187, v16
	global_store_dwordx4 v[60:61], v[56:59], off
	global_store_dwordx4 v[82:83], v[20:23], off nt
	global_store_dwordx4 v[82:83], v[24:27], off offset:16 nt
	v_cvt_pk_bf16_f32 v19, v22, v23
	v_cvt_pk_bf16_f32 v18, v20, v21
	s_nop 0
	v_lshl_add_u64 v[22:23], v[28:29], 1, s[24:25]
	v_cvt_pk_bf16_f32 v20, v24, v25
	v_cvt_pk_bf16_f32 v21, v26, v27
	global_store_dwordx4 v[22:23], v[18:21], off
	s_and_saveexec_b64 s[0:1], vcc
	s_cbranch_execz .LBB0_1331
	v_lshl_add_u64 v[18:19], v[80:81], 2, s[10:11]
	s_waitcnt lgkmcnt(0)
	v_add_f32_e32 v16, v16, v17
	global_atomic_add_f32 v[18:19], v16, off
.LBB0_1331:
	s_or_b64 exec, exec, s[0:1]
	s_waitcnt vmcnt(12)
	v_mov_b64_e32 v[40:41], v[228:229]
	v_mov_b64_e32 v[42:43], v[230:231]
	v_mov_b64_e32 v[44:45], v[232:233]
	v_mov_b64_e32 v[46:47], v[234:235]
	v_mov_b64_e32 v[32:33], v[236:237]
	v_mov_b64_e32 v[34:35], v[238:239]
	v_mov_b64_e32 v[36:37], v[240:241]
	v_mov_b64_e32 v[38:39], v[242:243]
	v_pk_add_f32 v[14:15], v[14:15], v[46:47]
	v_pk_add_f32 v[12:13], v[12:13], v[44:45]
	v_pk_add_f32 v[10:11], v[10:11], v[42:43]
	v_pk_add_f32 v[8:9], v[8:9], v[40:41]
	global_store_dwordx4 v[68:69], v[12:15], off nt
	global_store_dwordx4 v[68:69], v[8:11], off offset:16 nt
	v_cvt_pk_bf16_f32 v16, v12, v13
	v_cvt_pk_bf16_f32 v18, v8, v9
	v_pk_add_f32 v[6:7], v[6:7], v[38:39]
	v_mul_f32_e32 v13, v13, v13
	v_fmac_f32_e32 v13, v12, v12
	v_mul_f32_e32 v12, v15, v15
	v_fmac_f32_e32 v12, v14, v14
	v_mul_f32_e32 v9, v9, v9
	v_add_f32_e32 v12, v13, v12
	v_fmac_f32_e32 v9, v8, v8
	v_add_f32_e32 v8, v12, v9
	v_mul_f32_e32 v9, v11, v11
	v_fmac_f32_e32 v9, v10, v10
	v_pk_add_f32 v[4:5], v[4:5], v[36:37]
	s_waitcnt lgkmcnt(0)
	v_cvt_pk_bf16_f32 v17, v14, v15
	v_add_f32_e32 v14, v9, v8
	v_pk_add_f32 v[8:9], v[0:1], v[32:33]
	v_mul_f32_e32 v0, v5, v5
	v_mul_f32_e32 v1, v7, v7
	v_fmac_f32_e32 v0, v4, v4
	v_fmac_f32_e32 v1, v6, v6
	v_add_f32_e32 v0, v0, v1
	v_mul_f32_e32 v1, v9, v9
	v_cvt_pk_bf16_f32 v19, v10, v11
	v_pk_add_f32 v[10:11], v[2:3], v[34:35]
	v_fmac_f32_e32 v1, v8, v8
	v_add_f32_e32 v0, v0, v1
	v_mul_f32_e32 v1, v11, v11
	v_fmac_f32_e32 v1, v10, v10
	v_add_f32_e32 v0, v1, v0
	v_add_f32_e32 v0, v14, v0
	ds_bpermute_b32 v1, v186, v0
	v_lshlrev_b64 v[20:21], 10, v[64:65]
	v_lshl_add_u64 v[22:23], v[20:21], 0, v[162:163]
	v_lshl_add_u64 v[22:23], v[22:23], 1, s[24:25]
	v_lshl_add_u64 v[12:13], v[20:21], 0, v[160:161]
	s_waitcnt lgkmcnt(0)
	v_add_f32_e32 v0, v0, v1
	ds_bpermute_b32 v1, v187, v0
	global_store_dwordx4 v[22:23], v[16:19], off
	global_store_dwordx4 v[66:67], v[4:7], off nt
	global_store_dwordx4 v[66:67], v[8:11], off offset:16 nt
	v_cvt_pk_bf16_f32 v3, v6, v7
	v_cvt_pk_bf16_f32 v2, v4, v5
	s_nop 0
	v_lshl_add_u64 v[6:7], v[12:13], 1, s[24:25]
	v_cvt_pk_bf16_f32 v4, v8, v9
	v_cvt_pk_bf16_f32 v5, v10, v11
	global_store_dwordx4 v[6:7], v[2:5], off
	s_and_saveexec_b64 s[0:1], vcc
	s_cbranch_execz .LBB0_1333
	v_lshl_add_u64 v[2:3], v[64:65], 2, s[10:11]
	s_waitcnt lgkmcnt(0)
	v_add_f32_e32 v0, v0, v1
	global_atomic_add_f32 v[2:3], v0, off

; #define EPI_IT_ROW(it) EPI_ROW((it) >> 2, (it) & 3)
; #define EPI_PACK8(v0, v1) (u32x4){pk2((v0)[0], (v0)[1]), pk2((v0)[2], (v0)[3]), pk2((v1)[0], (v1)[1]), pk2((v1)[2], (v1)[3])}
;     __device__ __forceinline__ void operator()(AccRef acc, const Unit& u, int wr, int wc, int fr, int fq) const {
;     ...
;         for (int bj = 0; bj < 2; ++bj) { const size_t p = (size_t)EPI_IT_ROW(0) * DM + EPI_COL(bj); xc[bj][0] = *(const f32x4*)(xin + p); xc[bj][1] = *(const f32x4*)(xin + p + 4); }
; #pragma unroll
;         for (int it = 0; it < 8; ++it) { const int ai = it >> 2, m = it & 3, row = EPI_IT_ROW(it);
;             if (it + 1 < 8) {
; #pragma unroll
;                 for (int bj = 0; bj < 2; ++bj) { const size_t p = (size_t)EPI_IT_ROW(it + 1) * DM + EPI_COL(bj); xn[bj][0] = *(const f32x4*)(xin + p); xn[bj][1] = *(const f32x4*)(xin + p + 4); } }
;             float q = 0.f;
; #pragma unroll
;             for (int bj = 0; bj < 2; ++bj) { const size_t p = (size_t)row * DM + EPI_COL(bj);
;                 const f32x4 x0 = xc[bj][0] + acc[ai][bj][m][0], x1 = xc[bj][1] + acc[ai][bj][m][1];
;                 __builtin_nontemporal_store(x0, (f32x4*)(xout + p)); __builtin_nontemporal_store(x1, (f32x4*)(xout + p + 4));
;                 *(u32x4*)(xb + p) = EPI_PACK8(x0, x1);
;                 q += EPI_SQ8(x0, x1); }
;             q += __shfl_xor(q, 16); q += __shfl_xor(q, 32);
;             if (fq == 0) atomicAdd(ssout + row, q);
; #pragma unroll
;             for (int bj = 0; bj < 2; ++bj) { xc[bj][0] = xn[bj][0]; xc[bj][1] = xn[bj][1]; } }
.LBB0_1652:
	s_lshl_b32 s0, s60, 8
	v_mov_b32_e32 v128, v180
	v_mov_b32_e32 v186, v177
	s_add_i32 s0, s0, s38
	v_and_b32_e32 v202, 64, v185
	v_add_u32_e32 v164, s0, v128
	s_lshl_b32 s0, s59, 8
	s_or_b32 s0, s0, s39
	v_ashrrev_i32_e32 v165, 31, v164
	v_lshl_add_u32 v162, v186, 3, s0
	v_lshlrev_b64 v[128:129], 12, v[164:165]
	v_ashrrev_i32_e32 v163, 31, v162
	v_add_u32_e32 v160, 0x80, v162
	v_lshl_add_u64 v[128:129], s[48:49], 0, v[128:129]
	v_lshlrev_b64 v[130:131], 2, v[162:163]
	v_ashrrev_i32_e32 v161, 31, v160
	v_lshl_add_u64 v[178:179], v[128:129], 0, v[130:131]
	v_lshlrev_b64 v[132:133], 2, v[160:161]
	global_load_dwordx4 v[170:173], v[178:179], off offset:16
	global_load_dwordx4 v[188:191], v[178:179], off
	v_lshl_add_u64 v[200:201], v[128:129], 0, v[132:133]
	global_load_dwordx4 v[192:195], v[200:201], off
	global_load_dwordx4 v[196:199], v[200:201], off offset:16
	v_add_u32_e32 v166, 16, v164
	v_ashrrev_i32_e32 v167, 31, v166
	v_lshlrev_b64 v[128:129], 12, v[166:167]
	v_lshl_add_u64 v[128:129], s[48:49], 0, v[128:129]
	v_lshl_add_u64 v[174:175], v[128:129], 0, v[130:131]
	v_lshl_add_u64 v[168:169], v[128:129], 0, v[132:133]
	global_load_dwordx4 v[136:139], v[174:175], off offset:16
	global_load_dwordx4 v[140:143], v[174:175], off
	global_load_dwordx4 v[128:131], v[168:169], off offset:16
	global_load_dwordx4 v[132:135], v[168:169], off
	v_add_u32_e32 v244, 32, v164
	v_ashrrev_i32_e32 v245, 31, v244
	v_lshlrev_b64 v[246:247], 12, v[244:245]
	v_lshl_add_u64 v[246:247], s[48:49], 0, v[246:247]
	v_lshl_add_u64 v[248:249], v[162:163], 2, v[246:247]
	v_lshl_add_u64 v[250:251], v[160:161], 2, v[246:247]
	global_load_dwordx4 v[206:209], v[248:249], off offset:16
	global_load_dwordx4 v[210:213], v[248:249], off
	global_load_dwordx4 v[214:217], v[250:251], off offset:16
	global_load_dwordx4 v[218:221], v[250:251], off
	v_add_u32_e32 v244, 48, v164
	v_ashrrev_i32_e32 v245, 31, v244
	v_lshlrev_b64 v[246:247], 12, v[244:245]
	v_lshl_add_u64 v[246:247], s[48:49], 0, v[246:247]
	v_lshl_add_u64 v[248:249], v[162:163], 2, v[246:247]
	v_lshl_add_u64 v[250:251], v[160:161], 2, v[246:247]
	global_load_dwordx4 v[228:231], v[248:249], off offset:16
	global_load_dwordx4 v[232:235], v[248:249], off
	global_load_dwordx4 v[236:239], v[250:251], off offset:16
	global_load_dwordx4 v[240:243], v[250:251], off
	v_xor_b32_e32 v187, 16, v185
	v_add_u32_e32 v202, 64, v202
	v_cmp_lt_i32_e64 s[0:1], v187, v202
	v_cmp_eq_u32_e32 vcc, 0, v186
	v_xor_b32_e32 v203, 32, v185
	v_cndmask_b32_e64 v186, v185, v187, s[0:1]
	v_lshlrev_b32_e32 v186, 2, v186
	v_cmp_lt_i32_e64 s[0:1], v203, v202
	s_waitcnt vmcnt(8)
	v_pk_add_f32 v[122:123], v[122:123], v[172:173]
	v_pk_add_f32 v[126:127], v[126:127], v[190:191]
	v_pk_add_f32 v[124:125], v[124:125], v[188:189]
	v_pk_add_f32 v[118:119], v[118:119], v[194:195]
	v_pk_add_f32 v[116:117], v[116:117], v[192:193]
	v_pk_add_f32 v[120:121], v[120:121], v[170:171]
	v_pk_add_f32 v[170:171], v[112:113], v[196:197]
	global_store_dwordx4 v[178:179], v[124:127], off nt
	global_store_dwordx4 v[178:179], v[120:123], off offset:16 nt
	v_cvt_pk_bf16_f32 v112, v124, v125
	v_cvt_pk_bf16_f32 v113, v126, v127
	v_mul_f32_e32 v178, v117, v117
	v_mul_f32_e32 v125, v125, v125
	v_mul_f32_e32 v127, v127, v127
	v_mul_f32_e32 v179, v119, v119
	v_pk_add_f32 v[172:173], v[114:115], v[198:199]
	v_cvt_pk_bf16_f32 v114, v120, v121
	v_cvt_pk_bf16_f32 v115, v122, v123
	v_mul_f32_e32 v121, v121, v121
	v_mul_f32_e32 v123, v123, v123
	v_mul_f32_e32 v189, v171, v171
	v_fmac_f32_e32 v125, v124, v124
	v_fmac_f32_e32 v127, v126, v126
	v_fmac_f32_e32 v178, v116, v116
	v_fmac_f32_e32 v179, v118, v118
	v_mul_f32_e32 v190, v173, v173
	v_fmac_f32_e32 v121, v120, v120
	v_fmac_f32_e32 v123, v122, v122
	v_fmac_f32_e32 v189, v170, v170
	v_add_f32_e32 v120, v125, v127
	v_add_f32_e32 v122, v178, v179
	v_fmac_f32_e32 v190, v172, v172
	v_add_f32_e32 v120, v120, v121
	v_add_f32_e32 v121, v122, v189
	v_add_f32_e32 v120, v123, v120
	v_add_f32_e32 v121, v190, v121
	v_add_f32_e32 v120, v120, v121
	ds_bpermute_b32 v121, v186, v120
	v_cndmask_b32_e64 v187, v185, v203, s[0:1]
	v_lshlrev_b64 v[202:203], 10, v[164:165]
	v_lshl_add_u64 v[204:205], v[202:203], 0, v[162:163]
	v_lshl_add_u64 v[204:205], v[204:205], 1, s[30:31]
	global_store_dwordx4 v[204:205], v[112:115], off
	global_store_dwordx4 v[200:201], v[116:119], off nt
	global_store_dwordx4 v[200:201], v[170:173], off offset:16 nt
	s_waitcnt lgkmcnt(0)
	v_add_f32_e32 v112, v120, v121
	v_lshlrev_b32_e32 v187, 2, v187
	ds_bpermute_b32 v113, v187, v112
	v_lshl_add_u64 v[202:203], v[202:203], 0, v[160:161]
	v_lshl_add_u64 v[114:115], v[202:203], 1, s[30:31]
	v_cvt_pk_bf16_f32 v188, v116, v117
	v_cvt_pk_bf16_f32 v189, v118, v119
	v_cvt_pk_bf16_f32 v190, v170, v171
	v_cvt_pk_bf16_f32 v191, v172, v173
	global_store_dwordx4 v[114:115], v[188:191], off
	s_and_saveexec_b64 s[0:1], vcc
	s_cbranch_execz .LBB0_1654
	v_lshl_add_u64 v[114:115], v[164:165], 2, s[12:13]
	s_waitcnt lgkmcnt(0)
	v_add_f32_e32 v112, v112, v113
	global_atomic_add_f32 v[114:115], v112, off
